# plus: full cluster barriers issue the L1 invalidate with the first poll
# baseline (speedup 1.0000x reference)
.LBB0_137:
	s_or_b64 exec, exec, s[8:9]
	buffer_inv sc1
	s_add_u32 s6, s4, 0x1000000
	s_addc_u32 s7, s5, 0
	s_cmp_gt_u32 s10, 63
	s_cselect_b64 s[8:9], -1, 0
	s_lshl_b32 s13, s11, 2
	s_add_u32 s4, s4, s13
	s_addc_u32 s5, s5, 0
	s_add_u32 s10, s4, 0x102c400
	s_addc_u32 s11, s5, 0
	s_and_b32 s4, s12, 15
	s_add_u32 s5, s6, s13
	s_addc_u32 s12, s7, 0
	s_add_u32 s5, s5, 0x2c300
	s_addc_u32 s12, s12, 0
	s_cmp_lg_u32 s4, 0
	s_cselect_b32 s13, s12, 0
	s_cselect_b32 s12, s5, 0
	v_cmp_eq_u32_e32 vcc, 0, v3
	s_cmp_eq_u64 s[12:13], 0
	s_mov_b64 s[14:15], 0
	v_cndmask_b32_e64 v3, 0, 1, vcc
	s_mov_b32 s24, 1
	s_cselect_b64 s[16:17], -1, 0
	v_mov_b32_e32 v2, 0
	v_cmp_ne_u32_e64 s[4:5], 1, v3
	v_mov_b32_e32 v3, 1
	s_branch .LBB0_139

.LBB0_155:
	s_andn2_b64 vcc, exec, s[18:19]
	s_cbranch_vccz .LBB0_157
	v_mov_b32_e32 v2, 0
	v_mov_b32_e32 v3, 1
	global_store_dword v2, v3, s[6:7] sc1
.LBB0_157:
	s_waitcnt vmcnt(0)
	s_waitcnt vmcnt(0)
.LBB0_158:
	s_or_b64 exec, exec, s[0:1]
	s_mov_b64 s[0:1], s[82:83]
	v_mov_b32_e32 v34, v0
	s_mov_b32 s2, s73
	s_mov_b32 s7, s72
	s_barrier
	s_load_dwordx2 s[2:3], s[0:1], 0x18
	v_lshlrev_b32_e32 v2, 3, v34
	v_and_b32_e32 v35, 0x3f8, v2
	v_mov_b32_e32 v149, 0
	v_lshlrev_b32_e32 v148, 2, v35
	s_waitcnt lgkmcnt(0)
	v_lshl_add_u64 v[6:7], s[2:3], 0, v[148:149]
	global_load_dwordx4 v[2:5], v148, s[2:3] offset:16
	global_load_dwordx4 v[14:17], v148, s[2:3]
	s_movk_i32 s2, 0x1000
	v_add_co_u32_e32 v30, vcc, s2, v6
	s_mov_b64 s[4:5], 0x1000
	s_nop 0
	v_addc_co_u32_e32 v31, vcc, 0, v7, vcc
	v_lshl_add_u64 v[26:27], v[6:7], 0, s[4:5]
	s_mov_b64 s[4:5], 0x2000
	v_add_co_u32_e32 v32, vcc, 0x2000, v6
	v_lshl_add_u64 v[28:29], v[6:7], 0, s[4:5]
	s_nop 0
	v_addc_co_u32_e32 v33, vcc, 0, v7, vcc
	global_load_dwordx4 v[18:21], v[30:31], off
	global_load_dwordx4 v[22:25], v[32:33], off
	global_load_dwordx4 v[10:13], v[26:27], off offset:16
	global_load_dwordx4 v[6:9], v[28:29], off offset:16
	s_load_dwordx2 s[0:1], s[0:1], 0x90
	s_lshl_b32 s2, s7, 3
	s_and_b32 s2, s2, 56
	s_bfe_u32 s3, s7, 0x30003
	s_or_b32 s6, s2, s3
	s_waitcnt lgkmcnt(0)
	s_add_u32 s2, s0, 0xdc00000
	v_ashrrev_i32_e32 v26, 3, v34
	s_addc_u32 s3, s1, 0
	s_andn2_b32 s7, s7, 63
	v_and_b32_e32 v26, -16, v26
	v_add_u32_e32 v26, s7, v26
	v_lshl_add_u32 v30, s6, 8, v26
	v_and_b32_e32 v27, 0xff0, v30
	v_cmp_ne_u32_e32 vcc, 0, v27
	v_ashrrev_i32_e32 v31, 31, v30
	v_lshlrev_b32_e32 v148, 1, v35
	v_mov_b32_e32 v186, 0
	v_mov_b32_e32 v184, 0
	v_mov_b32_e32 v187, 0
	v_mov_b32_e32 v185, 0
	v_mov_b32_e32 v180, 0
	v_mov_b32_e32 v178, 0
	v_mov_b32_e32 v181, 0
	v_mov_b32_e32 v179, 0
	v_mov_b32_e32 v194, 0
	v_mov_b32_e32 v195, 0
	v_mov_b32_e32 v154, 0
	v_mov_b32_e32 v155, 0
	v_mov_b32_e32 v190, 0
	v_mov_b32_e32 v191, 0
	v_mov_b32_e32 v192, 0
	v_mov_b32_e32 v193, 0
	s_and_saveexec_b64 s[4:5], vcc
	s_cbranch_execz .LBB0_160
	v_lshlrev_b64 v[32:33], 11, v[30:31]
	v_mov_b32_e32 v29, 0
	v_mov_b32_e32 v28, v148
	v_lshl_add_u64 v[32:33], s[2:3], 0, v[32:33]
	v_lshl_add_u64 v[28:29], v[32:33], 0, v[28:29]
	global_load_dwordx4 v[32:35], v[28:29], off offset:-4096
	global_load_dwordx4 v[36:39], v[28:29], off offset:-2048
	s_waitcnt vmcnt(1)
	v_lshlrev_b32_e32 v154, 16, v32
	v_and_b32_e32 v194, 0xffff0000, v32
	v_lshlrev_b32_e32 v155, 16, v33
	v_and_b32_e32 v195, 0xffff0000, v33
	v_lshlrev_b32_e32 v192, 16, v34
	v_and_b32_e32 v190, 0xffff0000, v34
	v_lshlrev_b32_e32 v193, 16, v35
	v_and_b32_e32 v191, 0xffff0000, v35
	s_waitcnt vmcnt(0)
	v_lshlrev_b32_e32 v186, 16, v36
	v_and_b32_e32 v184, 0xffff0000, v36
	v_lshlrev_b32_e32 v187, 16, v37
	v_and_b32_e32 v185, 0xffff0000, v37
	v_lshlrev_b32_e32 v180, 16, v38
	v_and_b32_e32 v178, 0xffff0000, v38
	v_lshlrev_b32_e32 v181, 16, v39
	v_and_b32_e32 v179, 0xffff0000, v39

.LBB0_282:
	s_or_b64 exec, exec, s[8:9]
	v_mov_b32_e32 v2, 0
	global_load_dword v3, v2, s[2:3] sc1
	buffer_inv sc1
	s_waitcnt vmcnt(0)
	v_cmp_lt_u32_e32 vcc, 15, v3
	s_cbranch_vccnz .LBB0_293
	s_add_u32 s4, s4, 0x1000000
	s_addc_u32 s5, s5, 0
	s_mov_b32 s12, 1
	s_branch .LBB0_285

.LBB0_291:
	s_andn2_b64 vcc, exec, s[8:9]
	s_cbranch_vccz .LBB0_293
	v_mov_b32_e32 v2, 0
	v_mov_b32_e32 v3, 1
	global_store_dword v2, v3, s[4:5] sc1
.LBB0_293:
	s_waitcnt vmcnt(0)
	s_waitcnt vmcnt(0)
.LBB0_294:
	s_or_b64 exec, exec, s[0:1]
	s_mov_b64 s[0:1], s[82:83]
	v_mov_b32_e32 v2, v0
	s_mov_b32 s5, s72
	s_mov_b32 s2, s73
	s_barrier
	s_load_dwordx2 s[2:3], s[0:1], 0x90
	v_readfirstlane_b32 s4, v2
	s_lshl_b32 s0, s5, 3
	s_and_b32 s0, s0, 56
	s_bfe_u32 s1, s5, 0x30003
	s_ashr_i32 s4, s4, 3
	s_or_b32 s8, s0, s1
	s_and_b32 s1, s5, 0xffffffc0
	s_and_b32 s4, s4, -8
	s_lshl_b32 s0, s8, 8
	s_add_i32 s4, s1, s4
	s_add_i32 s6, s4, s0
	s_ashr_i32 s7, s6, 31
	s_lshl_b64 s[0:1], s[6:7], 11
	v_and_b32_e32 v126, 63, v2
	s_waitcnt lgkmcnt(0)
	s_add_u32 s0, s2, s0
	s_addc_u32 s1, s3, s1
	v_lshlrev_b32_e32 v30, 4, v126
	v_mov_b32_e32 v31, 0
	v_lshl_add_u64 v[2:3], s[0:1], 0, v[30:31]
	s_mov_b32 s0, 0x3001000
	v_add_co_u32_e32 v60, vcc, s0, v2
	s_mov_b64 s[0:1], 0x3000000
	s_nop 0
	v_addc_co_u32_e32 v61, vcc, 0, v3, vcc
	global_load_dwordx4 v[18:21], v[60:61], off offset:-4096
	v_lshl_add_u64 v[4:5], v[2:3], 0, s[0:1]
	global_load_dwordx4 v[22:25], v[4:5], off offset:1024
	global_load_dwordx4 v[32:35], v[4:5], off offset:2048
	global_load_dwordx4 v[36:39], v[4:5], off offset:3072
	s_mov_b32 s0, 0x3002000
	v_add_co_u32_e32 v62, vcc, s0, v2
	s_mov_b32 s1, 0x3003000
	s_nop 0
	v_addc_co_u32_e32 v63, vcc, 0, v3, vcc
	v_add_co_u32_e32 v64, vcc, s1, v2
	s_lshl_b32 s5, s8, 19
	s_nop 0
	v_addc_co_u32_e32 v65, vcc, 0, v3, vcc
	global_load_dwordx4 v[40:43], v[60:61], off
	global_load_dwordx4 v[44:47], v[60:61], off offset:1024
	global_load_dwordx4 v[48:51], v[60:61], off offset:2048
	global_load_dwordx4 v[52:55], v[60:61], off offset:3072
	global_load_dwordx4 v[56:59], v[64:65], off offset:-4096
	global_load_dwordx4 v[26:29], v[62:63], off offset:1024
	global_load_dwordx4 v[14:17], v[62:63], off offset:2048
	global_load_dwordx4 v[10:13], v[62:63], off offset:3072
	global_load_dwordx4 v[6:9], v[64:65], off
	global_load_dwordx4 v[2:5], v[64:65], off offset:1024
	s_add_u32 s5, s2, s5
	s_addc_u32 s8, s3, 0
	s_lshl_b32 s4, s4, 10
	s_and_b32 s0, s4, 0x3e000
	s_add_u32 s4, s5, s0
	s_addc_u32 s5, s8, 0
	s_mov_b32 s9, 0x42fe0000
	s_lshl_b64 s[0:1], s[6:7], 2
	s_add_u32 s0, s2, s0
	s_addc_u32 s1, s3, s1
	s_add_u32 s0, s0, 0xfc00000
	s_addc_u32 s1, s1, 0
	s_lshl_b64 s[6:7], s[6:7], 4
	s_mov_b32 s8, 0x40c0c00
	s_add_u32 s2, s2, s6
	s_mov_b32 s6, 0xa800000
	s_addc_u32 s3, s3, s7
	s_add_u32 s2, s2, 0xda00000
	s_addc_u32 s3, s3, 0
	s_waitcnt vmcnt(12)
	v_lshlrev_b32_e32 v148, 16, v22
	v_lshlrev_b32_e32 v140, 16, v18
	v_and_b32_e32 v141, 0xffff0000, v18
	v_lshlrev_b32_e32 v142, 16, v19
	v_and_b32_e32 v143, 0xffff0000, v19
	v_max3_f32 v18, |v140|, 0, |v141|
	v_lshlrev_b32_e32 v144, 16, v20
	v_and_b32_e32 v145, 0xffff0000, v20
	v_max3_f32 v18, v18, |v142|, |v143|
	v_lshlrev_b32_e32 v146, 16, v21
	v_and_b32_e32 v147, 0xffff0000, v21
	v_max3_f32 v18, v18, |v144|, |v145|
	v_and_b32_e32 v149, 0xffff0000, v22
	v_max3_f32 v18, v18, |v146|, |v147|
	v_lshlrev_b32_e32 v134, 16, v23
	v_and_b32_e32 v132, 0xffff0000, v23
	v_max3_f32 v18, v18, |v148|, |v149|
	v_lshlrev_b32_e32 v150, 16, v24
	v_and_b32_e32 v151, 0xffff0000, v24
	v_max3_f32 v18, v18, |v134|, |v132|
	v_lshlrev_b32_e32 v133, 16, v25
	v_and_b32_e32 v131, 0xffff0000, v25
	v_max3_f32 v18, v18, |v150|, |v151|
	v_max3_f32 v18, v18, |v133|, |v131|
	ds_swizzle_b32 v19, v18 offset:swizzle(SWAP,1)
	s_waitcnt vmcnt(11)
	v_lshlrev_b32_e32 v130, 16, v32
	v_and_b32_e32 v128, 0xffff0000, v32
	v_lshlrev_b32_e32 v122, 16, v33
	v_and_b32_e32 v119, 0xffff0000, v33
	s_waitcnt lgkmcnt(0)
	v_max_f32_e32 v19, v19, v19
	v_max_f32_e32 v18, v18, v19
	ds_swizzle_b32 v19, v18 offset:swizzle(SWAP,2)
	v_max3_f32 v20, |v130|, 0, |v128|
	v_lshlrev_b32_e32 v129, 16, v34
	v_and_b32_e32 v127, 0xffff0000, v34
	v_max3_f32 v20, v20, |v122|, |v119|
	s_waitcnt lgkmcnt(0)
	v_max_f32_e32 v19, v19, v19
	v_max_f32_e32 v18, v18, v19
	ds_swizzle_b32 v19, v18 offset:swizzle(SWAP,4)
	v_lshlrev_b32_e32 v123, 16, v35
	v_and_b32_e32 v121, 0xffff0000, v35
	v_max3_f32 v20, v20, |v129|, |v127|
	s_waitcnt vmcnt(10)
	v_lshlrev_b32_e32 v117, 16, v36
	s_waitcnt lgkmcnt(0)
	v_max_f32_e32 v19, v19, v19
	v_max_f32_e32 v18, v18, v19
	ds_swizzle_b32 v19, v18 offset:swizzle(SWAP,8)
	v_and_b32_e32 v116, 0xffff0000, v36
	v_max3_f32 v20, v20, |v123|, |v121|
	v_lshlrev_b32_e32 v113, 16, v37
	v_and_b32_e32 v114, 0xffff0000, v37
	s_waitcnt lgkmcnt(0)
	v_max_f32_e32 v19, v19, v19
	v_max_f32_e32 v30, v18, v19
	v_max3_f32 v18, v20, |v117|, |v116|
	v_lshlrev_b32_e32 v120, 16, v38
	v_and_b32_e32 v118, 0xffff0000, v38
	v_max3_f32 v18, v18, |v113|, |v114|
	v_lshlrev_b32_e32 v115, 16, v39
	v_and_b32_e32 v112, 0xffff0000, v39
	v_max3_f32 v18, v18, |v120|, |v118|
	ds_swizzle_b32 v32, v30 offset:swizzle(SWAP,16)
	v_max3_f32 v33, v18, |v115|, |v112|
	ds_swizzle_b32 v34, v33 offset:swizzle(SWAP,1)
	s_waitcnt vmcnt(9)
	v_lshlrev_b32_e32 v111, 16, v40
	v_and_b32_e32 v109, 0xffff0000, v40
	s_waitcnt lgkmcnt(1)
	v_max_f32_e32 v32, v32, v32
	v_max_f32_e32 v30, v30, v32
	s_waitcnt lgkmcnt(0)
	v_max_f32_e32 v32, v34, v34
	v_max_f32_e32 v32, v33, v32
	v_lshlrev_b32_e32 v106, 16, v41
	v_and_b32_e32 v105, 0xffff0000, v41
	v_max3_f32 v35, |v111|, 0, |v109|
	global_load_dwordx4 v[22:25], v[64:65], off offset:2048
	global_load_dwordx4 v[18:21], v[64:65], off offset:3072
	ds_swizzle_b32 v33, v32 offset:swizzle(SWAP,2)
	v_lshlrev_b32_e32 v110, 16, v42
	v_and_b32_e32 v108, 0xffff0000, v42
	v_max3_f32 v35, v35, |v106|, |v105|
	v_lshlrev_b32_e32 v107, 16, v43
	v_and_b32_e32 v104, 0xffff0000, v43
	v_max3_f32 v35, v35, |v110|, |v108|
	v_max3_f32 v35, v35, |v107|, |v104|
	s_waitcnt vmcnt(10)
	v_lshlrev_b32_e32 v103, 16, v44
	v_and_b32_e32 v101, 0xffff0000, v44
	v_lshlrev_b32_e32 v99, 16, v45
	v_and_b32_e32 v95, 0xffff0000, v45
	v_max3_f32 v35, v35, |v103|, |v101|
	v_lshlrev_b32_e32 v102, 16, v46
	v_and_b32_e32 v100, 0xffff0000, v46
	v_max3_f32 v35, v35, |v99|, |v95|
	s_waitcnt lgkmcnt(0)
	v_max_f32_e32 v33, v33, v33
	v_lshlrev_b32_e32 v98, 16, v47
	v_and_b32_e32 v94, 0xffff0000, v47
	v_max3_f32 v35, v35, |v102|, |v100|
	v_max_f32_e32 v32, v32, v33
	v_max3_f32 v35, v35, |v98|, |v94|
	ds_swizzle_b32 v33, v32 offset:swizzle(SWAP,4)
	ds_swizzle_b32 v36, v35 offset:swizzle(SWAP,1)
	v_mov_b32_e32 v34, v30
	s_nop 1
	v_permlane32_swap_b32_e32 v30, v34
	s_waitcnt lgkmcnt(1)
	v_max_f32_e32 v33, v33, v33
	s_waitcnt lgkmcnt(0)
	v_max_f32_e32 v36, v36, v36
	v_max_f32_e32 v32, v32, v33
	v_max_f32_e32 v35, v35, v36
	ds_swizzle_b32 v33, v32 offset:swizzle(SWAP,8)
	ds_swizzle_b32 v36, v35 offset:swizzle(SWAP,2)
	v_max_f32_e32 v34, v34, v34
	v_max_f32_e32 v30, v30, v30
	v_max_f32_e32 v137, v30, v34
	s_waitcnt lgkmcnt(1)
	v_max_f32_e32 v30, v33, v33
	s_waitcnt lgkmcnt(0)
	v_max_f32_e32 v33, v36, v36
	s_waitcnt vmcnt(9)
	v_lshlrev_b32_e32 v93, 16, v48
	v_and_b32_e32 v91, 0xffff0000, v48
	v_max_f32_e32 v33, v35, v33
	v_lshlrev_b32_e32 v89, 16, v49
	v_and_b32_e32 v87, 0xffff0000, v49
	v_max3_f32 v35, |v93|, 0, |v91|
	v_lshlrev_b32_e32 v92, 16, v50
	v_and_b32_e32 v90, 0xffff0000, v50
	v_max3_f32 v35, v35, |v89|, |v87|
	v_lshlrev_b32_e32 v88, 16, v51
	v_and_b32_e32 v86, 0xffff0000, v51
	v_max3_f32 v35, v35, |v92|, |v90|
	v_max3_f32 v35, v35, |v88|, |v86|
	s_waitcnt vmcnt(8)
	v_lshlrev_b32_e32 v85, 16, v52
	v_and_b32_e32 v83, 0xffff0000, v52
	v_lshlrev_b32_e32 v81, 16, v53
	v_and_b32_e32 v79, 0xffff0000, v53
	v_max3_f32 v35, v35, |v85|, |v83|
	v_lshlrev_b32_e32 v84, 16, v54
	v_and_b32_e32 v82, 0xffff0000, v54
	v_max3_f32 v35, v35, |v81|, |v79|
	v_lshlrev_b32_e32 v80, 16, v55
	v_and_b32_e32 v78, 0xffff0000, v55
	v_max3_f32 v35, v35, |v84|, |v82|
	ds_swizzle_b32 v34, v33 offset:swizzle(SWAP,4)
	v_max3_f32 v35, v35, |v80|, |v78|
	ds_swizzle_b32 v36, v35 offset:swizzle(SWAP,1)
	v_max_f32_e32 v30, v32, v30
	ds_swizzle_b32 v32, v30 offset:swizzle(SWAP,16)
	s_waitcnt lgkmcnt(2)
	v_max_f32_e32 v34, v34, v34
	v_max_f32_e32 v33, v33, v34
	s_waitcnt lgkmcnt(1)
	v_max_f32_e32 v36, v36, v36
	ds_swizzle_b32 v34, v33 offset:swizzle(SWAP,8)
	v_max_f32_e32 v35, v35, v36
	ds_swizzle_b32 v36, v35 offset:swizzle(SWAP,2)
	s_waitcnt lgkmcnt(2)
	v_max_f32_e32 v32, v32, v32
	v_max_f32_e32 v138, v30, v32
	s_waitcnt lgkmcnt(1)
	v_max_f32_e32 v30, v34, v34
	v_max_f32_e32 v30, v33, v30
	s_waitcnt lgkmcnt(0)
	v_max_f32_e32 v33, v36, v36
	s_waitcnt vmcnt(7)
	v_lshlrev_b32_e32 v77, 16, v56
	v_and_b32_e32 v75, 0xffff0000, v56
	v_max_f32_e32 v33, v35, v33
	v_lshlrev_b32_e32 v72, 16, v57
	v_and_b32_e32 v71, 0xffff0000, v57
	v_max3_f32 v35, |v77|, 0, |v75|
	v_lshlrev_b32_e32 v76, 16, v58
	v_and_b32_e32 v74, 0xffff0000, v58
	v_max3_f32 v35, v35, |v72|, |v71|
	v_lshlrev_b32_e32 v73, 16, v59
	v_and_b32_e32 v70, 0xffff0000, v59
	v_max3_f32 v35, v35, |v76|, |v74|
	v_max3_f32 v35, v35, |v73|, |v70|
	s_waitcnt vmcnt(6)
	v_lshlrev_b32_e32 v69, 16, v26
	v_and_b32_e32 v67, 0xffff0000, v26
	v_lshlrev_b32_e32 v65, 16, v27
	v_and_b32_e32 v63, 0xffff0000, v27
	v_max3_f32 v26, v35, |v69|, |v67|
	v_lshlrev_b32_e32 v68, 16, v28
	v_and_b32_e32 v66, 0xffff0000, v28
	v_max3_f32 v26, v26, |v65|, |v63|
	v_lshlrev_b32_e32 v64, 16, v29
	v_and_b32_e32 v62, 0xffff0000, v29
	v_max3_f32 v26, v26, |v68|, |v66|
	v_max3_f32 v26, v26, |v64|, |v62|
	s_waitcnt vmcnt(5)
	v_lshlrev_b32_e32 v61, 16, v14
	v_and_b32_e32 v59, 0xffff0000, v14
	ds_swizzle_b32 v27, v26 offset:swizzle(SWAP,1)
	v_lshlrev_b32_e32 v57, 16, v15
	v_and_b32_e32 v55, 0xffff0000, v15
	v_max3_f32 v14, |v61|, 0, |v59|
	v_lshlrev_b32_e32 v60, 16, v16
	v_and_b32_e32 v58, 0xffff0000, v16
	v_max3_f32 v14, v14, |v57|, |v55|
	v_lshlrev_b32_e32 v56, 16, v17
	v_and_b32_e32 v54, 0xffff0000, v17
	v_max3_f32 v14, v14, |v60|, |v58|
	v_max3_f32 v14, v14, |v56|, |v54|
	s_waitcnt vmcnt(4)
	v_lshlrev_b32_e32 v53, 16, v10
	v_and_b32_e32 v51, 0xffff0000, v10
	v_lshlrev_b32_e32 v49, 16, v11
	v_and_b32_e32 v47, 0xffff0000, v11
	v_max3_f32 v10, v14, |v53|, |v51|
	s_waitcnt lgkmcnt(0)
	v_max_f32_e32 v27, v27, v27
	v_lshlrev_b32_e32 v52, 16, v12
	v_and_b32_e32 v50, 0xffff0000, v12
	v_max3_f32 v10, v10, |v49|, |v47|
	v_max_f32_e32 v26, v26, v27
	v_lshlrev_b32_e32 v48, 16, v13
	v_and_b32_e32 v46, 0xffff0000, v13
	v_max3_f32 v10, v10, |v52|, |v50|
	ds_swizzle_b32 v27, v26 offset:swizzle(SWAP,2)
	v_max3_f32 v10, v10, |v48|, |v46|
	ds_swizzle_b32 v11, v10 offset:swizzle(SWAP,1)
	ds_swizzle_b32 v34, v33 offset:swizzle(SWAP,4)
	ds_swizzle_b32 v32, v30 offset:swizzle(SWAP,16)
	s_waitcnt lgkmcnt(3)
	v_max_f32_e32 v27, v27, v27
	v_max_f32_e32 v26, v26, v27
	s_waitcnt lgkmcnt(2)
	v_max_f32_e32 v11, v11, v11
	ds_swizzle_b32 v27, v26 offset:swizzle(SWAP,4)
	v_max_f32_e32 v10, v10, v11
	ds_swizzle_b32 v11, v10 offset:swizzle(SWAP,2)
	s_waitcnt lgkmcnt(3)
	v_max_f32_e32 v34, v34, v34
	v_max_f32_e32 v33, v33, v34
	ds_swizzle_b32 v34, v33 offset:swizzle(SWAP,8)
	s_waitcnt lgkmcnt(2)
	v_max_f32_e32 v12, v27, v27
	v_max_f32_e32 v12, v26, v12
	s_waitcnt lgkmcnt(1)
	v_max_f32_e32 v11, v11, v11
	ds_swizzle_b32 v13, v12 offset:swizzle(SWAP,8)
	v_max_f32_e32 v10, v10, v11
	ds_swizzle_b32 v11, v10 offset:swizzle(SWAP,4)
	s_waitcnt lgkmcnt(2)
	v_max_f32_e32 v28, v34, v34
	v_max_f32_e32 v28, v33, v28
	ds_swizzle_b32 v29, v28 offset:swizzle(SWAP,16)
	s_waitcnt lgkmcnt(2)
	v_max_f32_e32 v13, v13, v13
	v_max_f32_e32 v12, v12, v13
	s_waitcnt lgkmcnt(1)
	v_max_f32_e32 v11, v11, v11
	ds_swizzle_b32 v13, v12 offset:swizzle(SWAP,16)
	v_max_f32_e32 v10, v10, v11
	ds_swizzle_b32 v11, v10 offset:swizzle(SWAP,8)
	s_waitcnt vmcnt(3)
	v_lshlrev_b32_e32 v45, 16, v6
	v_and_b32_e32 v43, 0xffff0000, v6
	v_max_f32_e32 v32, v32, v32
	s_waitcnt lgkmcnt(2)
	v_max_f32_e32 v29, v29, v29
	v_lshlrev_b32_e32 v40, 16, v7
	v_and_b32_e32 v39, 0xffff0000, v7
	v_max3_f32 v6, |v45|, 0, |v43|
	s_waitcnt vmcnt(1)
	v_lshlrev_b32_e32 v27, 16, v22
	v_and_b32_e32 v26, 0xffff0000, v22
	v_max_f32_e32 v135, v30, v32
	v_max_f32_e32 v124, v28, v29
	v_lshlrev_b32_e32 v44, 16, v8
	v_and_b32_e32 v42, 0xffff0000, v8
	v_max3_f32 v6, v6, |v40|, |v39|
	v_lshlrev_b32_e32 v32, 16, v5
	v_and_b32_e32 v28, 0xffff0000, v5
	v_lshlrev_b32_e32 v17, 16, v23
	v_and_b32_e32 v15, 0xffff0000, v23
	v_max3_f32 v5, |v27|, 0, |v26|
	v_lshlrev_b32_e32 v41, 16, v9
	v_and_b32_e32 v38, 0xffff0000, v9
	v_max3_f32 v6, v6, |v44|, |v42|
	v_lshlrev_b32_e32 v23, 16, v24
	v_and_b32_e32 v22, 0xffff0000, v24
	v_max3_f32 v5, v5, |v17|, |v15|
	s_waitcnt lgkmcnt(1)
	v_max_f32_e32 v13, v13, v13
	v_max3_f32 v6, v6, |v41|, |v38|
	v_lshlrev_b32_e32 v37, 16, v2
	v_and_b32_e32 v35, 0xffff0000, v2
	v_lshlrev_b32_e32 v16, 16, v25
	v_and_b32_e32 v14, 0xffff0000, v25
	v_max3_f32 v5, v5, |v23|, |v22|
	v_max_f32_e32 v96, v12, v13
	v_lshlrev_b32_e32 v33, 16, v3
	v_and_b32_e32 v29, 0xffff0000, v3
	v_lshlrev_b32_e32 v36, 16, v4
	v_and_b32_e32 v34, 0xffff0000, v4
	v_max3_f32 v2, v6, |v37|, |v35|
	s_waitcnt lgkmcnt(0)
	v_max_f32_e32 v4, v11, v11
	v_max3_f32 v5, v5, |v16|, |v14|
	s_waitcnt vmcnt(0)
	v_lshlrev_b32_e32 v13, 16, v18
	v_and_b32_e32 v11, 0xffff0000, v18
	v_max3_f32 v2, v2, |v33|, |v29|
	v_lshlrev_b32_e32 v9, 16, v19
	v_and_b32_e32 v7, 0xffff0000, v19
	v_max3_f32 v5, v5, |v13|, |v11|
	v_max3_f32 v2, v2, |v36|, |v34|
	v_max_f32_e32 v4, v10, v4
	v_lshlrev_b32_e32 v12, 16, v20
	v_and_b32_e32 v10, 0xffff0000, v20
	v_max3_f32 v5, v5, |v9|, |v7|
	v_max3_f32 v2, v2, |v32|, |v28|
	v_lshlrev_b32_e32 v8, 16, v21
	v_and_b32_e32 v6, 0xffff0000, v21
	v_max3_f32 v5, v5, |v12|, |v10|
	ds_swizzle_b32 v3, v2 offset:swizzle(SWAP,1)
	v_max3_f32 v5, v5, |v8|, |v6|
	ds_swizzle_b32 v18, v5 offset:swizzle(SWAP,1)
	ds_swizzle_b32 v19, v4 offset:swizzle(SWAP,16)
	v_lshlrev_b32_e32 v30, 3, v126
	s_waitcnt lgkmcnt(2)
	v_max_f32_e32 v3, v3, v3
	v_max_f32_e32 v2, v2, v3
	s_waitcnt lgkmcnt(1)
	v_max_f32_e32 v18, v18, v18
	ds_swizzle_b32 v3, v2 offset:swizzle(SWAP,2)
	v_max_f32_e32 v5, v5, v18
	ds_swizzle_b32 v18, v5 offset:swizzle(SWAP,2)
	s_waitcnt lgkmcnt(2)
	v_max_f32_e32 v19, v19, v19
	v_max_f32_e32 v24, v4, v19
	s_waitcnt lgkmcnt(1)
	v_max_f32_e32 v3, v3, v3
	v_max_f32_e32 v2, v2, v3
	s_waitcnt lgkmcnt(0)
	v_max_f32_e32 v18, v18, v18
	ds_swizzle_b32 v3, v2 offset:swizzle(SWAP,4)
	v_max_f32_e32 v5, v5, v18
	ds_swizzle_b32 v18, v5 offset:swizzle(SWAP,4)
	v_mov_b32_e32 v139, v138
	v_mov_b32_e32 v136, v135
	s_waitcnt lgkmcnt(1)
	v_max_f32_e32 v3, v3, v3
	v_max_f32_e32 v2, v2, v3
	s_waitcnt lgkmcnt(0)
	v_max_f32_e32 v4, v18, v18
	ds_swizzle_b32 v3, v2 offset:swizzle(SWAP,8)
	v_max_f32_e32 v4, v5, v4
	ds_swizzle_b32 v5, v4 offset:swizzle(SWAP,8)
	v_mov_b32_e32 v125, v124
	v_mov_b32_e32 v97, v96
	s_waitcnt lgkmcnt(1)
	v_max_f32_e32 v3, v3, v3
	v_max_f32_e32 v2, v2, v3
	s_waitcnt lgkmcnt(0)
	v_max_f32_e32 v5, v5, v5
	ds_swizzle_b32 v3, v2 offset:swizzle(SWAP,16)
	v_max_f32_e32 v4, v4, v5
	ds_swizzle_b32 v5, v4 offset:swizzle(SWAP,16)
	v_mov_b32_e32 v25, v24
	v_permlane32_swap_b32_e32 v138, v139
	s_waitcnt lgkmcnt(1)
	v_max_f32_e32 v3, v3, v3
	v_max_f32_e32 v20, v2, v3
	s_waitcnt lgkmcnt(0)
	v_max_f32_e32 v2, v5, v5
	v_max_f32_e32 v18, v4, v2
	v_lshl_add_u64 v[4:5], s[4:5], 0, v[30:31]
	v_div_scale_f32 v30, s[4:5], v137, v137, s9
	v_rcp_f32_e32 v152, v30
	s_mov_b64 s[4:5], 0xa800000
	v_lshl_add_u64 v[2:3], v[4:5], 0, s[4:5]
	v_cmp_eq_u32_e64 s[4:5], 0, v126
	v_fma_f32 v126, -v30, v152, 1.0
	v_fmac_f32_e32 v152, v126, v152
	v_div_scale_f32 v126, vcc, s9, v137, s9
	v_mul_f32_e32 v153, v126, v152
	v_fma_f32 v154, -v30, v153, v126
	v_fmac_f32_e32 v153, v154, v152
	v_fma_f32 v30, -v30, v153, v126
	v_div_fmas_f32 v30, v30, v152, v153
	v_div_fixup_f32 v30, v30, v137, s9
	v_cmp_lt_f32_e32 vcc, 0, v137
	v_mov_b32_e32 v21, v20
	v_mov_b32_e32 v19, v18
	v_cndmask_b32_e32 v30, 0, v30, vcc
	v_mul_f32_e32 v126, v30, v140
	v_mul_f32_e32 v140, v30, v141
	v_rndne_f32_e32 v140, v140
	v_mul_f32_e32 v141, v30, v144
	v_mul_f32_e32 v144, v30, v145
	v_mul_f32_e32 v142, v30, v142
	v_mul_f32_e32 v143, v30, v143
	v_rndne_f32_e32 v126, v126
	v_cvt_i32_f32_e32 v140, v140
	v_rndne_f32_e32 v144, v144
	v_rndne_f32_e32 v142, v142
	v_mul_f32_e32 v145, v30, v146
	v_rndne_f32_e32 v143, v143
	v_mul_f32_e32 v146, v30, v147
	v_cvt_i32_f32_e32 v126, v126
	v_rndne_f32_e32 v141, v141
	v_cvt_i32_f32_e32 v144, v144
	v_cvt_i32_f32_sdwa v142, v142 dst_sel:WORD_1 dst_unused:UNUSED_PAD src0_sel:DWORD
	v_rndne_f32_e32 v145, v145
	v_cvt_i32_f32_e32 v143, v143
	v_rndne_f32_e32 v146, v146
	v_cvt_i32_f32_e32 v141, v141
	v_cvt_i32_f32_sdwa v145, v145 dst_sel:WORD_1 dst_unused:UNUSED_PAD src0_sel:DWORD
	v_cvt_i32_f32_e32 v146, v146
	v_lshlrev_b32_e32 v140, 8, v140
	v_and_b32_e32 v140, 0xff00, v140
	v_lshlrev_b32_e32 v144, 8, v144
	v_and_b32_e32 v142, 0xff0000, v142
	v_perm_b32 v126, v143, v126, s8
	v_and_b32_e32 v144, 0xff00, v144
	v_and_b32_e32 v145, 0xff0000, v145
	v_or3_b32 v140, v126, v140, v142
	v_perm_b32 v126, v146, v141, s8
	v_add_co_u32_e32 v4, vcc, s6, v4
	v_or3_b32 v141, v126, v144, v145
	s_nop 0
	v_addc_co_u32_e32 v5, vcc, 0, v5, vcc
	global_store_dwordx2 v[4:5], v[140:141], off
	v_mul_f32_e32 v5, v30, v149
	v_mul_f32_e32 v4, v30, v148
	v_rndne_f32_e32 v5, v5
	v_mul_f32_e32 v140, v30, v151
	v_mul_f32_e32 v134, v30, v134
	v_mul_f32_e32 v132, v30, v132
	v_rndne_f32_e32 v4, v4
	v_cvt_i32_f32_e32 v5, v5
	v_mul_f32_e32 v126, v30, v150
	v_rndne_f32_e32 v140, v140
	v_rndne_f32_e32 v134, v134
	v_mul_f32_e32 v133, v30, v133
	v_rndne_f32_e32 v132, v132
	v_mul_f32_e32 v30, v30, v131
	v_cvt_i32_f32_e32 v4, v4
	v_rndne_f32_e32 v126, v126
	v_cvt_i32_f32_e32 v140, v140
	v_cvt_i32_f32_sdwa v134, v134 dst_sel:WORD_1 dst_unused:UNUSED_PAD src0_sel:DWORD
	v_rndne_f32_e32 v133, v133
	v_cvt_i32_f32_e32 v132, v132
	v_rndne_f32_e32 v30, v30
	v_cvt_i32_f32_e32 v126, v126
	v_cvt_i32_f32_sdwa v133, v133 dst_sel:WORD_1 dst_unused:UNUSED_PAD src0_sel:DWORD
	v_cvt_i32_f32_e32 v30, v30
	v_lshlrev_b32_e32 v5, 8, v5
	v_and_b32_e32 v5, 0xff00, v5
	v_lshlrev_b32_e32 v140, 8, v140
	v_and_b32_e32 v134, 0xff0000, v134
	v_perm_b32 v4, v132, v4, s8
	v_and_b32_e32 v140, 0xff00, v140
	v_and_b32_e32 v131, 0xff0000, v133
	v_or3_b32 v4, v4, v5, v134
	v_perm_b32 v5, v30, v126, s8
	v_permlane32_swap_b32_e32 v135, v136
	v_permlane32_swap_b32_e32 v124, v125
	v_permlane32_swap_b32_e32 v96, v97
	v_permlane32_swap_b32_e32 v24, v25
	v_permlane32_swap_b32_e32 v20, v21
	v_permlane32_swap_b32_e32 v18, v19
	v_or3_b32 v5, v5, v140, v131
	global_store_dwordx2 v[2:3], v[4:5], off offset:512
	s_and_saveexec_b64 s[6:7], s[4:5]
	s_cbranch_execz .LBB0_296
	global_load_dwordx4 v[140:143], v31, s[2:3]
	s_waitcnt vmcnt(0)
	v_mov_b32_e32 v4, v141
	v_mov_b32_e32 v5, v142
	v_mov_b32_e32 v141, v143
	v_pk_add_f32 v[4:5], v[4:5], v[140:141]
	s_nop 0
	v_add_f32_e32 v4, v4, v5
	v_mov_b32_e32 v5, 0x358637bd
	v_fmac_f32_e32 v5, 0x3a800000, v4
	v_rsq_f32_e32 v4, v5
	v_mul_f32_e32 v5, 0x3c010204, v137
	v_mul_f32_e32 v4, v5, v4
	global_store_dword v31, v4, s[0:1]

.LBB0_530:
	s_or_b64 exec, exec, s[8:9]
	v_mov_b32_e32 v2, 0
	global_load_dword v3, v2, s[2:3] sc1
	buffer_inv sc1
	s_waitcnt vmcnt(0)
	v_cmp_lt_u32_e32 vcc, 27, v3
	s_cbranch_vccnz .LBB0_541
	s_add_u32 s4, s4, 0x1000000
	s_addc_u32 s5, s5, 0
	s_mov_b32 s12, 1
	s_branch .LBB0_533

.LBB0_539:
	s_andn2_b64 vcc, exec, s[8:9]
	s_cbranch_vccz .LBB0_541
	v_mov_b32_e32 v2, 0
	v_mov_b32_e32 v3, 1
	global_store_dword v2, v3, s[4:5] sc1
.LBB0_541:
	s_waitcnt vmcnt(0)
	s_waitcnt vmcnt(0)
.LBB0_542:
	s_or_b64 exec, exec, s[0:1]
	s_mov_b64 s[0:1], s[82:83]
	v_mov_b32_e32 v2, v0
	s_mov_b32 s5, s72
	s_mov_b32 s2, s73
	s_barrier
	s_load_dwordx2 s[2:3], s[0:1], 0x90
	v_readfirstlane_b32 s4, v2
	s_lshl_b32 s0, s5, 3
	s_and_b32 s0, s0, 56
	s_bfe_u32 s1, s5, 0x30003
	s_ashr_i32 s4, s4, 3
	s_or_b32 s8, s0, s1
	s_and_b32 s1, s5, 0xffffffc0
	s_and_b32 s4, s4, -8
	s_lshl_b32 s0, s8, 8
	s_add_i32 s4, s1, s4
	s_add_i32 s6, s4, s0
	s_ashr_i32 s7, s6, 31
	s_lshl_b64 s[0:1], s[6:7], 11
	v_and_b32_e32 v126, 63, v2
	s_waitcnt lgkmcnt(0)
	s_add_u32 s0, s2, s0
	s_addc_u32 s1, s3, s1
	v_lshlrev_b32_e32 v30, 4, v126
	v_mov_b32_e32 v31, 0
	v_lshl_add_u64 v[2:3], s[0:1], 0, v[30:31]
	s_mov_b32 s0, 0x3001000
	v_add_co_u32_e32 v60, vcc, s0, v2
	s_mov_b64 s[0:1], 0x3000000
	s_nop 0
	v_addc_co_u32_e32 v61, vcc, 0, v3, vcc
	global_load_dwordx4 v[18:21], v[60:61], off offset:-4096
	v_lshl_add_u64 v[4:5], v[2:3], 0, s[0:1]
	global_load_dwordx4 v[22:25], v[4:5], off offset:1024
	global_load_dwordx4 v[32:35], v[4:5], off offset:2048
	global_load_dwordx4 v[36:39], v[4:5], off offset:3072
	s_mov_b32 s0, 0x3002000
	v_add_co_u32_e32 v62, vcc, s0, v2
	s_mov_b32 s1, 0x3003000
	s_nop 0
	v_addc_co_u32_e32 v63, vcc, 0, v3, vcc
	v_add_co_u32_e32 v64, vcc, s1, v2
	s_mul_i32 s8, s8, 0x160000
	s_nop 0
	v_addc_co_u32_e32 v65, vcc, 0, v3, vcc
	global_load_dwordx4 v[40:43], v[60:61], off
	global_load_dwordx4 v[44:47], v[60:61], off offset:1024
	global_load_dwordx4 v[48:51], v[60:61], off offset:2048
	global_load_dwordx4 v[52:55], v[60:61], off offset:3072
	global_load_dwordx4 v[56:59], v[64:65], off offset:-4096
	global_load_dwordx4 v[26:29], v[62:63], off offset:1024
	global_load_dwordx4 v[14:17], v[62:63], off offset:2048
	global_load_dwordx4 v[10:13], v[62:63], off offset:3072
	global_load_dwordx4 v[6:9], v[64:65], off
	global_load_dwordx4 v[2:5], v[64:65], off offset:1024
	s_add_u32 s5, s2, s8
	s_addc_u32 s8, s3, 0
	s_lshl_b32 s4, s4, 10
	s_and_b32 s0, s4, 0x3e000
	s_add_u32 s4, s5, s0
	s_addc_u32 s5, s8, 0
	s_mov_b32 s9, 0x42fe0000
	s_lshl_b64 s[0:1], s[6:7], 2
	s_add_u32 s0, s2, s0
	s_addc_u32 s1, s3, s1
	s_add_u32 s0, s0, 0xfc00000
	s_addc_u32 s1, s1, 0
	s_lshl_b64 s[6:7], s[6:7], 4
	s_mov_b32 s8, 0x40c0c00
	s_add_u32 s2, s2, s6
	s_mov_b32 s6, 0x5000000
	s_addc_u32 s3, s3, s7
	s_add_u32 s2, s2, 0xda00000
	s_addc_u32 s3, s3, 0
	s_waitcnt vmcnt(12)
	v_lshlrev_b32_e32 v148, 16, v22
	v_lshlrev_b32_e32 v140, 16, v18
	v_and_b32_e32 v141, 0xffff0000, v18
	v_lshlrev_b32_e32 v142, 16, v19
	v_and_b32_e32 v143, 0xffff0000, v19
	v_max3_f32 v18, |v140|, 0, |v141|
	v_lshlrev_b32_e32 v144, 16, v20
	v_and_b32_e32 v145, 0xffff0000, v20
	v_max3_f32 v18, v18, |v142|, |v143|
	v_lshlrev_b32_e32 v146, 16, v21
	v_and_b32_e32 v147, 0xffff0000, v21
	v_max3_f32 v18, v18, |v144|, |v145|
	v_and_b32_e32 v149, 0xffff0000, v22
	v_max3_f32 v18, v18, |v146|, |v147|
	v_lshlrev_b32_e32 v134, 16, v23
	v_and_b32_e32 v132, 0xffff0000, v23
	v_max3_f32 v18, v18, |v148|, |v149|
	v_lshlrev_b32_e32 v150, 16, v24
	v_and_b32_e32 v151, 0xffff0000, v24
	v_max3_f32 v18, v18, |v134|, |v132|
	v_lshlrev_b32_e32 v133, 16, v25
	v_and_b32_e32 v131, 0xffff0000, v25
	v_max3_f32 v18, v18, |v150|, |v151|
	v_max3_f32 v18, v18, |v133|, |v131|
	ds_swizzle_b32 v19, v18 offset:swizzle(SWAP,1)
	s_waitcnt vmcnt(11)
	v_lshlrev_b32_e32 v130, 16, v32
	v_and_b32_e32 v128, 0xffff0000, v32
	v_lshlrev_b32_e32 v122, 16, v33
	v_and_b32_e32 v119, 0xffff0000, v33
	s_waitcnt lgkmcnt(0)
	v_max_f32_e32 v19, v19, v19
	v_max_f32_e32 v18, v18, v19
	ds_swizzle_b32 v19, v18 offset:swizzle(SWAP,2)
	v_max3_f32 v20, |v130|, 0, |v128|
	v_lshlrev_b32_e32 v129, 16, v34
	v_and_b32_e32 v127, 0xffff0000, v34
	v_max3_f32 v20, v20, |v122|, |v119|
	s_waitcnt lgkmcnt(0)
	v_max_f32_e32 v19, v19, v19
	v_max_f32_e32 v18, v18, v19
	ds_swizzle_b32 v19, v18 offset:swizzle(SWAP,4)
	v_lshlrev_b32_e32 v123, 16, v35
	v_and_b32_e32 v121, 0xffff0000, v35
	v_max3_f32 v20, v20, |v129|, |v127|
	s_waitcnt vmcnt(10)
	v_lshlrev_b32_e32 v117, 16, v36
	s_waitcnt lgkmcnt(0)
	v_max_f32_e32 v19, v19, v19
	v_max_f32_e32 v18, v18, v19
	ds_swizzle_b32 v19, v18 offset:swizzle(SWAP,8)
	v_and_b32_e32 v116, 0xffff0000, v36
	v_max3_f32 v20, v20, |v123|, |v121|
	v_lshlrev_b32_e32 v113, 16, v37
	v_and_b32_e32 v114, 0xffff0000, v37
	s_waitcnt lgkmcnt(0)
	v_max_f32_e32 v19, v19, v19
	v_max_f32_e32 v30, v18, v19
	v_max3_f32 v18, v20, |v117|, |v116|
	v_lshlrev_b32_e32 v120, 16, v38
	v_and_b32_e32 v118, 0xffff0000, v38
	v_max3_f32 v18, v18, |v113|, |v114|
	v_lshlrev_b32_e32 v115, 16, v39
	v_and_b32_e32 v112, 0xffff0000, v39
	v_max3_f32 v18, v18, |v120|, |v118|
	ds_swizzle_b32 v32, v30 offset:swizzle(SWAP,16)
	v_max3_f32 v33, v18, |v115|, |v112|
	ds_swizzle_b32 v34, v33 offset:swizzle(SWAP,1)
	s_waitcnt vmcnt(9)
	v_lshlrev_b32_e32 v111, 16, v40
	v_and_b32_e32 v109, 0xffff0000, v40
	s_waitcnt lgkmcnt(1)
	v_max_f32_e32 v32, v32, v32
	v_max_f32_e32 v30, v30, v32
	s_waitcnt lgkmcnt(0)
	v_max_f32_e32 v32, v34, v34
	v_max_f32_e32 v32, v33, v32
	v_lshlrev_b32_e32 v106, 16, v41
	v_and_b32_e32 v105, 0xffff0000, v41
	v_max3_f32 v35, |v111|, 0, |v109|
	global_load_dwordx4 v[22:25], v[64:65], off offset:2048
	global_load_dwordx4 v[18:21], v[64:65], off offset:3072
	ds_swizzle_b32 v33, v32 offset:swizzle(SWAP,2)
	v_lshlrev_b32_e32 v110, 16, v42
	v_and_b32_e32 v108, 0xffff0000, v42
	v_max3_f32 v35, v35, |v106|, |v105|
	v_lshlrev_b32_e32 v107, 16, v43
	v_and_b32_e32 v104, 0xffff0000, v43
	v_max3_f32 v35, v35, |v110|, |v108|
	v_max3_f32 v35, v35, |v107|, |v104|
	s_waitcnt vmcnt(10)
	v_lshlrev_b32_e32 v103, 16, v44
	v_and_b32_e32 v101, 0xffff0000, v44
	v_lshlrev_b32_e32 v99, 16, v45
	v_and_b32_e32 v95, 0xffff0000, v45
	v_max3_f32 v35, v35, |v103|, |v101|
	v_lshlrev_b32_e32 v102, 16, v46
	v_and_b32_e32 v100, 0xffff0000, v46
	v_max3_f32 v35, v35, |v99|, |v95|
	s_waitcnt lgkmcnt(0)
	v_max_f32_e32 v33, v33, v33
	v_lshlrev_b32_e32 v98, 16, v47
	v_and_b32_e32 v94, 0xffff0000, v47
	v_max3_f32 v35, v35, |v102|, |v100|
	v_max_f32_e32 v32, v32, v33
	v_max3_f32 v35, v35, |v98|, |v94|
	ds_swizzle_b32 v33, v32 offset:swizzle(SWAP,4)
	ds_swizzle_b32 v36, v35 offset:swizzle(SWAP,1)
	v_mov_b32_e32 v34, v30
	s_nop 1
	v_permlane32_swap_b32_e32 v30, v34
	s_waitcnt lgkmcnt(1)
	v_max_f32_e32 v33, v33, v33
	s_waitcnt lgkmcnt(0)
	v_max_f32_e32 v36, v36, v36
	v_max_f32_e32 v32, v32, v33
	v_max_f32_e32 v35, v35, v36
	ds_swizzle_b32 v33, v32 offset:swizzle(SWAP,8)
	ds_swizzle_b32 v36, v35 offset:swizzle(SWAP,2)
	v_max_f32_e32 v34, v34, v34
	v_max_f32_e32 v30, v30, v30
	v_max_f32_e32 v137, v30, v34
	s_waitcnt lgkmcnt(1)
	v_max_f32_e32 v30, v33, v33
	s_waitcnt lgkmcnt(0)
	v_max_f32_e32 v33, v36, v36
	s_waitcnt vmcnt(9)
	v_lshlrev_b32_e32 v93, 16, v48
	v_and_b32_e32 v91, 0xffff0000, v48
	v_max_f32_e32 v33, v35, v33
	v_lshlrev_b32_e32 v89, 16, v49
	v_and_b32_e32 v87, 0xffff0000, v49
	v_max3_f32 v35, |v93|, 0, |v91|
	v_lshlrev_b32_e32 v92, 16, v50
	v_and_b32_e32 v90, 0xffff0000, v50
	v_max3_f32 v35, v35, |v89|, |v87|
	v_lshlrev_b32_e32 v88, 16, v51
	v_and_b32_e32 v86, 0xffff0000, v51
	v_max3_f32 v35, v35, |v92|, |v90|
	v_max3_f32 v35, v35, |v88|, |v86|
	s_waitcnt vmcnt(8)
	v_lshlrev_b32_e32 v85, 16, v52
	v_and_b32_e32 v83, 0xffff0000, v52
	v_lshlrev_b32_e32 v81, 16, v53
	v_and_b32_e32 v79, 0xffff0000, v53
	v_max3_f32 v35, v35, |v85|, |v83|
	v_lshlrev_b32_e32 v84, 16, v54
	v_and_b32_e32 v82, 0xffff0000, v54
	v_max3_f32 v35, v35, |v81|, |v79|
	v_lshlrev_b32_e32 v80, 16, v55
	v_and_b32_e32 v78, 0xffff0000, v55
	v_max3_f32 v35, v35, |v84|, |v82|
	ds_swizzle_b32 v34, v33 offset:swizzle(SWAP,4)
	v_max3_f32 v35, v35, |v80|, |v78|
	ds_swizzle_b32 v36, v35 offset:swizzle(SWAP,1)
	v_max_f32_e32 v30, v32, v30
	ds_swizzle_b32 v32, v30 offset:swizzle(SWAP,16)
	s_waitcnt lgkmcnt(2)
	v_max_f32_e32 v34, v34, v34
	v_max_f32_e32 v33, v33, v34
	s_waitcnt lgkmcnt(1)
	v_max_f32_e32 v36, v36, v36
	ds_swizzle_b32 v34, v33 offset:swizzle(SWAP,8)
	v_max_f32_e32 v35, v35, v36
	ds_swizzle_b32 v36, v35 offset:swizzle(SWAP,2)
	s_waitcnt lgkmcnt(2)
	v_max_f32_e32 v32, v32, v32
	v_max_f32_e32 v138, v30, v32
	s_waitcnt lgkmcnt(1)
	v_max_f32_e32 v30, v34, v34
	v_max_f32_e32 v30, v33, v30
	s_waitcnt lgkmcnt(0)
	v_max_f32_e32 v33, v36, v36
	s_waitcnt vmcnt(7)
	v_lshlrev_b32_e32 v77, 16, v56
	v_and_b32_e32 v75, 0xffff0000, v56
	v_max_f32_e32 v33, v35, v33
	v_lshlrev_b32_e32 v72, 16, v57
	v_and_b32_e32 v71, 0xffff0000, v57
	v_max3_f32 v35, |v77|, 0, |v75|
	v_lshlrev_b32_e32 v76, 16, v58
	v_and_b32_e32 v74, 0xffff0000, v58
	v_max3_f32 v35, v35, |v72|, |v71|
	v_lshlrev_b32_e32 v73, 16, v59
	v_and_b32_e32 v70, 0xffff0000, v59
	v_max3_f32 v35, v35, |v76|, |v74|
	v_max3_f32 v35, v35, |v73|, |v70|
	s_waitcnt vmcnt(6)
	v_lshlrev_b32_e32 v69, 16, v26
	v_and_b32_e32 v67, 0xffff0000, v26
	v_lshlrev_b32_e32 v65, 16, v27
	v_and_b32_e32 v63, 0xffff0000, v27
	v_max3_f32 v26, v35, |v69|, |v67|
	v_lshlrev_b32_e32 v68, 16, v28
	v_and_b32_e32 v66, 0xffff0000, v28
	v_max3_f32 v26, v26, |v65|, |v63|
	v_lshlrev_b32_e32 v64, 16, v29
	v_and_b32_e32 v62, 0xffff0000, v29
	v_max3_f32 v26, v26, |v68|, |v66|
	v_max3_f32 v26, v26, |v64|, |v62|
	s_waitcnt vmcnt(5)
	v_lshlrev_b32_e32 v61, 16, v14
	v_and_b32_e32 v59, 0xffff0000, v14
	ds_swizzle_b32 v27, v26 offset:swizzle(SWAP,1)
	v_lshlrev_b32_e32 v57, 16, v15
	v_and_b32_e32 v55, 0xffff0000, v15
	v_max3_f32 v14, |v61|, 0, |v59|
	v_lshlrev_b32_e32 v60, 16, v16
	v_and_b32_e32 v58, 0xffff0000, v16
	v_max3_f32 v14, v14, |v57|, |v55|
	v_lshlrev_b32_e32 v56, 16, v17
	v_and_b32_e32 v54, 0xffff0000, v17
	v_max3_f32 v14, v14, |v60|, |v58|
	v_max3_f32 v14, v14, |v56|, |v54|
	s_waitcnt vmcnt(4)
	v_lshlrev_b32_e32 v53, 16, v10
	v_and_b32_e32 v51, 0xffff0000, v10
	v_lshlrev_b32_e32 v49, 16, v11
	v_and_b32_e32 v47, 0xffff0000, v11
	v_max3_f32 v10, v14, |v53|, |v51|
	s_waitcnt lgkmcnt(0)
	v_max_f32_e32 v27, v27, v27
	v_lshlrev_b32_e32 v52, 16, v12
	v_and_b32_e32 v50, 0xffff0000, v12
	v_max3_f32 v10, v10, |v49|, |v47|
	v_max_f32_e32 v26, v26, v27
	v_lshlrev_b32_e32 v48, 16, v13
	v_and_b32_e32 v46, 0xffff0000, v13
	v_max3_f32 v10, v10, |v52|, |v50|
	ds_swizzle_b32 v27, v26 offset:swizzle(SWAP,2)
	v_max3_f32 v10, v10, |v48|, |v46|
	ds_swizzle_b32 v11, v10 offset:swizzle(SWAP,1)
	ds_swizzle_b32 v34, v33 offset:swizzle(SWAP,4)
	ds_swizzle_b32 v32, v30 offset:swizzle(SWAP,16)
	s_waitcnt lgkmcnt(3)
	v_max_f32_e32 v27, v27, v27
	v_max_f32_e32 v26, v26, v27
	s_waitcnt lgkmcnt(2)
	v_max_f32_e32 v11, v11, v11
	ds_swizzle_b32 v27, v26 offset:swizzle(SWAP,4)
	v_max_f32_e32 v10, v10, v11
	ds_swizzle_b32 v11, v10 offset:swizzle(SWAP,2)
	s_waitcnt lgkmcnt(3)
	v_max_f32_e32 v34, v34, v34
	v_max_f32_e32 v33, v33, v34
	ds_swizzle_b32 v34, v33 offset:swizzle(SWAP,8)
	s_waitcnt lgkmcnt(2)
	v_max_f32_e32 v12, v27, v27
	v_max_f32_e32 v12, v26, v12
	s_waitcnt lgkmcnt(1)
	v_max_f32_e32 v11, v11, v11
	ds_swizzle_b32 v13, v12 offset:swizzle(SWAP,8)
	v_max_f32_e32 v10, v10, v11
	ds_swizzle_b32 v11, v10 offset:swizzle(SWAP,4)
	s_waitcnt lgkmcnt(2)
	v_max_f32_e32 v28, v34, v34
	v_max_f32_e32 v28, v33, v28
	ds_swizzle_b32 v29, v28 offset:swizzle(SWAP,16)
	s_waitcnt lgkmcnt(2)
	v_max_f32_e32 v13, v13, v13
	v_max_f32_e32 v12, v12, v13
	s_waitcnt lgkmcnt(1)
	v_max_f32_e32 v11, v11, v11
	ds_swizzle_b32 v13, v12 offset:swizzle(SWAP,16)
	v_max_f32_e32 v10, v10, v11
	ds_swizzle_b32 v11, v10 offset:swizzle(SWAP,8)
	s_waitcnt vmcnt(3)
	v_lshlrev_b32_e32 v45, 16, v6
	v_and_b32_e32 v43, 0xffff0000, v6
	v_max_f32_e32 v32, v32, v32
	s_waitcnt lgkmcnt(2)
	v_max_f32_e32 v29, v29, v29
	v_lshlrev_b32_e32 v40, 16, v7
	v_and_b32_e32 v39, 0xffff0000, v7
	v_max3_f32 v6, |v45|, 0, |v43|
	s_waitcnt vmcnt(1)
	v_lshlrev_b32_e32 v27, 16, v22
	v_and_b32_e32 v26, 0xffff0000, v22
	v_max_f32_e32 v135, v30, v32
	v_max_f32_e32 v124, v28, v29
	v_lshlrev_b32_e32 v44, 16, v8
	v_and_b32_e32 v42, 0xffff0000, v8
	v_max3_f32 v6, v6, |v40|, |v39|
	v_lshlrev_b32_e32 v32, 16, v5
	v_and_b32_e32 v28, 0xffff0000, v5
	v_lshlrev_b32_e32 v17, 16, v23
	v_and_b32_e32 v15, 0xffff0000, v23
	v_max3_f32 v5, |v27|, 0, |v26|
	v_lshlrev_b32_e32 v41, 16, v9
	v_and_b32_e32 v38, 0xffff0000, v9
	v_max3_f32 v6, v6, |v44|, |v42|
	v_lshlrev_b32_e32 v23, 16, v24
	v_and_b32_e32 v22, 0xffff0000, v24
	v_max3_f32 v5, v5, |v17|, |v15|
	s_waitcnt lgkmcnt(1)
	v_max_f32_e32 v13, v13, v13
	v_max3_f32 v6, v6, |v41|, |v38|
	v_lshlrev_b32_e32 v37, 16, v2
	v_and_b32_e32 v35, 0xffff0000, v2
	v_lshlrev_b32_e32 v16, 16, v25
	v_and_b32_e32 v14, 0xffff0000, v25
	v_max3_f32 v5, v5, |v23|, |v22|
	v_max_f32_e32 v96, v12, v13
	v_lshlrev_b32_e32 v33, 16, v3
	v_and_b32_e32 v29, 0xffff0000, v3
	v_lshlrev_b32_e32 v36, 16, v4
	v_and_b32_e32 v34, 0xffff0000, v4
	v_max3_f32 v2, v6, |v37|, |v35|
	s_waitcnt lgkmcnt(0)
	v_max_f32_e32 v4, v11, v11
	v_max3_f32 v5, v5, |v16|, |v14|
	s_waitcnt vmcnt(0)
	v_lshlrev_b32_e32 v13, 16, v18
	v_and_b32_e32 v11, 0xffff0000, v18
	v_max3_f32 v2, v2, |v33|, |v29|
	v_lshlrev_b32_e32 v9, 16, v19
	v_and_b32_e32 v7, 0xffff0000, v19
	v_max3_f32 v5, v5, |v13|, |v11|
	v_max3_f32 v2, v2, |v36|, |v34|
	v_max_f32_e32 v4, v10, v4
	v_lshlrev_b32_e32 v12, 16, v20
	v_and_b32_e32 v10, 0xffff0000, v20
	v_max3_f32 v5, v5, |v9|, |v7|
	v_max3_f32 v2, v2, |v32|, |v28|
	v_lshlrev_b32_e32 v8, 16, v21
	v_and_b32_e32 v6, 0xffff0000, v21
	v_max3_f32 v5, v5, |v12|, |v10|
	ds_swizzle_b32 v3, v2 offset:swizzle(SWAP,1)
	v_max3_f32 v5, v5, |v8|, |v6|
	ds_swizzle_b32 v18, v5 offset:swizzle(SWAP,1)
	ds_swizzle_b32 v19, v4 offset:swizzle(SWAP,16)
	v_lshlrev_b32_e32 v30, 3, v126
	s_waitcnt lgkmcnt(2)
	v_max_f32_e32 v3, v3, v3
	v_max_f32_e32 v2, v2, v3
	s_waitcnt lgkmcnt(1)
	v_max_f32_e32 v18, v18, v18
	ds_swizzle_b32 v3, v2 offset:swizzle(SWAP,2)
	v_max_f32_e32 v5, v5, v18
	ds_swizzle_b32 v18, v5 offset:swizzle(SWAP,2)
	s_waitcnt lgkmcnt(2)
	v_max_f32_e32 v19, v19, v19
	v_max_f32_e32 v24, v4, v19
	s_waitcnt lgkmcnt(1)
	v_max_f32_e32 v3, v3, v3
	v_max_f32_e32 v2, v2, v3
	s_waitcnt lgkmcnt(0)
	v_max_f32_e32 v18, v18, v18
	ds_swizzle_b32 v3, v2 offset:swizzle(SWAP,4)
	v_max_f32_e32 v5, v5, v18
	ds_swizzle_b32 v18, v5 offset:swizzle(SWAP,4)
	v_mov_b32_e32 v139, v138
	v_mov_b32_e32 v136, v135
	s_waitcnt lgkmcnt(1)
	v_max_f32_e32 v3, v3, v3
	v_max_f32_e32 v2, v2, v3
	s_waitcnt lgkmcnt(0)
	v_max_f32_e32 v4, v18, v18
	ds_swizzle_b32 v3, v2 offset:swizzle(SWAP,8)
	v_max_f32_e32 v4, v5, v4
	ds_swizzle_b32 v5, v4 offset:swizzle(SWAP,8)
	v_mov_b32_e32 v125, v124
	v_mov_b32_e32 v97, v96
	s_waitcnt lgkmcnt(1)
	v_max_f32_e32 v3, v3, v3
	v_max_f32_e32 v2, v2, v3
	s_waitcnt lgkmcnt(0)
	v_max_f32_e32 v5, v5, v5
	ds_swizzle_b32 v3, v2 offset:swizzle(SWAP,16)
	v_max_f32_e32 v4, v4, v5
	ds_swizzle_b32 v5, v4 offset:swizzle(SWAP,16)
	v_mov_b32_e32 v25, v24
	v_permlane32_swap_b32_e32 v138, v139
	s_waitcnt lgkmcnt(1)
	v_max_f32_e32 v3, v3, v3
	v_max_f32_e32 v20, v2, v3
	s_waitcnt lgkmcnt(0)
	v_max_f32_e32 v2, v5, v5
	v_max_f32_e32 v18, v4, v2
	v_lshl_add_u64 v[4:5], s[4:5], 0, v[30:31]
	v_div_scale_f32 v30, s[4:5], v137, v137, s9
	v_rcp_f32_e32 v152, v30
	s_mov_b64 s[4:5], 0x5000000
	v_lshl_add_u64 v[2:3], v[4:5], 0, s[4:5]
	v_cmp_eq_u32_e64 s[4:5], 0, v126
	v_fma_f32 v126, -v30, v152, 1.0
	v_fmac_f32_e32 v152, v126, v152
	v_div_scale_f32 v126, vcc, s9, v137, s9
	v_mul_f32_e32 v153, v126, v152
	v_fma_f32 v154, -v30, v153, v126
	v_fmac_f32_e32 v153, v154, v152
	v_fma_f32 v30, -v30, v153, v126
	v_div_fmas_f32 v30, v30, v152, v153
	v_div_fixup_f32 v30, v30, v137, s9
	v_cmp_lt_f32_e32 vcc, 0, v137
	v_mov_b32_e32 v21, v20
	v_mov_b32_e32 v19, v18
	v_cndmask_b32_e32 v30, 0, v30, vcc
	v_mul_f32_e32 v126, v30, v140
	v_mul_f32_e32 v140, v30, v141
	v_rndne_f32_e32 v140, v140
	v_mul_f32_e32 v141, v30, v144
	v_mul_f32_e32 v144, v30, v145
	v_mul_f32_e32 v142, v30, v142
	v_mul_f32_e32 v143, v30, v143
	v_rndne_f32_e32 v126, v126
	v_cvt_i32_f32_e32 v140, v140
	v_rndne_f32_e32 v144, v144
	v_rndne_f32_e32 v142, v142
	v_mul_f32_e32 v145, v30, v146
	v_rndne_f32_e32 v143, v143
	v_mul_f32_e32 v146, v30, v147
	v_cvt_i32_f32_e32 v126, v126
	v_rndne_f32_e32 v141, v141
	v_cvt_i32_f32_e32 v144, v144
	v_cvt_i32_f32_sdwa v142, v142 dst_sel:WORD_1 dst_unused:UNUSED_PAD src0_sel:DWORD
	v_rndne_f32_e32 v145, v145
	v_cvt_i32_f32_e32 v143, v143
	v_rndne_f32_e32 v146, v146
	v_cvt_i32_f32_e32 v141, v141
	v_cvt_i32_f32_sdwa v145, v145 dst_sel:WORD_1 dst_unused:UNUSED_PAD src0_sel:DWORD
	v_cvt_i32_f32_e32 v146, v146
	v_lshlrev_b32_e32 v140, 8, v140
	v_and_b32_e32 v140, 0xff00, v140
	v_lshlrev_b32_e32 v144, 8, v144
	v_and_b32_e32 v142, 0xff0000, v142
	v_perm_b32 v126, v143, v126, s8
	v_and_b32_e32 v144, 0xff00, v144
	v_and_b32_e32 v145, 0xff0000, v145
	v_or3_b32 v140, v126, v140, v142
	v_perm_b32 v126, v146, v141, s8
	v_add_co_u32_e32 v4, vcc, s6, v4
	v_or3_b32 v141, v126, v144, v145
	s_nop 0
	v_addc_co_u32_e32 v5, vcc, 0, v5, vcc
	global_store_dwordx2 v[4:5], v[140:141], off
	v_mul_f32_e32 v5, v30, v149
	v_mul_f32_e32 v4, v30, v148
	v_rndne_f32_e32 v5, v5
	v_mul_f32_e32 v140, v30, v151
	v_mul_f32_e32 v134, v30, v134
	v_mul_f32_e32 v132, v30, v132
	v_rndne_f32_e32 v4, v4
	v_cvt_i32_f32_e32 v5, v5
	v_mul_f32_e32 v126, v30, v150
	v_rndne_f32_e32 v140, v140
	v_rndne_f32_e32 v134, v134
	v_mul_f32_e32 v133, v30, v133
	v_rndne_f32_e32 v132, v132
	v_mul_f32_e32 v30, v30, v131
	v_cvt_i32_f32_e32 v4, v4
	v_rndne_f32_e32 v126, v126
	v_cvt_i32_f32_e32 v140, v140
	v_cvt_i32_f32_sdwa v134, v134 dst_sel:WORD_1 dst_unused:UNUSED_PAD src0_sel:DWORD
	v_rndne_f32_e32 v133, v133
	v_cvt_i32_f32_e32 v132, v132
	v_rndne_f32_e32 v30, v30
	v_cvt_i32_f32_e32 v126, v126
	v_cvt_i32_f32_sdwa v133, v133 dst_sel:WORD_1 dst_unused:UNUSED_PAD src0_sel:DWORD
	v_cvt_i32_f32_e32 v30, v30
	v_lshlrev_b32_e32 v5, 8, v5
	v_and_b32_e32 v5, 0xff00, v5
	v_lshlrev_b32_e32 v140, 8, v140
	v_and_b32_e32 v134, 0xff0000, v134
	v_perm_b32 v4, v132, v4, s8
	v_and_b32_e32 v140, 0xff00, v140
	v_and_b32_e32 v131, 0xff0000, v133
	v_or3_b32 v4, v4, v5, v134
	v_perm_b32 v5, v30, v126, s8
	v_permlane32_swap_b32_e32 v135, v136
	v_permlane32_swap_b32_e32 v124, v125
	v_permlane32_swap_b32_e32 v96, v97
	v_permlane32_swap_b32_e32 v24, v25
	v_permlane32_swap_b32_e32 v20, v21
	v_permlane32_swap_b32_e32 v18, v19
	v_or3_b32 v5, v5, v140, v131
	global_store_dwordx2 v[2:3], v[4:5], off offset:512
	s_and_saveexec_b64 s[6:7], s[4:5]
	s_cbranch_execz .LBB0_544
	global_load_dwordx4 v[140:143], v31, s[2:3]
	s_waitcnt vmcnt(0)
	v_mov_b32_e32 v4, v141
	v_mov_b32_e32 v5, v142
	v_mov_b32_e32 v141, v143
	v_pk_add_f32 v[4:5], v[4:5], v[140:141]
	s_nop 0
	v_add_f32_e32 v4, v4, v5
	v_mov_b32_e32 v5, 0x358637bd
	v_fmac_f32_e32 v5, 0x3a800000, v4
	v_rsq_f32_e32 v4, v5
	v_mul_f32_e32 v5, 0x3c010204, v137
	v_mul_f32_e32 v4, v5, v4
	global_store_dword v31, v4, s[0:1]

.LBB0_795:
	s_or_b64 exec, exec, s[8:9]
	buffer_inv sc1
	s_add_u32 s6, s4, 0x1000000
	s_addc_u32 s7, s5, 0
	s_cmp_gt_u32 s10, 63
	s_cselect_b64 s[8:9], -1, 0
	s_lshl_b32 s13, s11, 2
	s_add_u32 s4, s4, s13
	s_addc_u32 s5, s5, 0
	s_add_u32 s10, s4, 0x1030400
	s_addc_u32 s11, s5, 0
	s_and_b32 s4, s12, 15
	s_add_u32 s5, s6, s13
	s_addc_u32 s12, s7, 0
	s_add_u32 s5, s5, 0x30300
	s_addc_u32 s12, s12, 0
	s_cmp_lg_u32 s4, 0
	s_cselect_b32 s13, s12, 0
	s_cselect_b32 s12, s5, 0
	v_cmp_eq_u32_e32 vcc, 0, v3
	s_cmp_eq_u64 s[12:13], 0
	s_mov_b64 s[14:15], 0
	v_cndmask_b32_e64 v3, 0, 1, vcc
	s_mov_b32 s24, 1
	s_cselect_b64 s[16:17], -1, 0
	v_mov_b32_e32 v2, 0
	v_cmp_ne_u32_e64 s[4:5], 1, v3
	v_mov_b32_e32 v3, 1
	s_branch .LBB0_797

.LBB0_813:
	s_andn2_b64 vcc, exec, s[18:19]
	s_cbranch_vccz .LBB0_815
	v_mov_b32_e32 v2, 0
	v_mov_b32_e32 v3, 1
	global_store_dword v2, v3, s[6:7] sc1
.LBB0_815:
	s_waitcnt vmcnt(0)
	s_waitcnt vmcnt(0)
.LBB0_816:
	s_or_b64 exec, exec, s[0:1]
	s_mov_b64 s[4:5], s[82:83]
	v_mov_b32_e32 v138, v0
	s_mov_b32 s0, s73
	s_mov_b32 s2, s72
	s_barrier
	s_lshl_b32 s3, s2, 3
	s_and_b32 s3, s3, 56
	s_bfe_u32 s6, s2, 0x30003
	s_or_b32 s3, s3, s6
	s_load_dwordx2 s[0:1], s[4:5], 0x90
	s_ashr_i32 s2, s2, 6
	s_lshl_b32 s3, s3, 2
	s_add_i32 s6, s3, s2
	s_ashr_i32 s2, s6, 6
	s_lshl_b32 s6, s6, 6
	s_and_b32 s64, s6, 0xfc0
	v_lshlrev_b32_e32 v32, 4, v138
	v_mov_b32_e32 v2, 0
	s_add_i32 s8, s64, 0xffffff80
	v_and_b32_e32 v4, 0x70, v32
	v_mov_b32_e32 v5, v2
	v_ashrrev_i32_e32 v33, 3, v138
	s_ashr_i32 s3, s2, 31
	s_waitcnt lgkmcnt(0)
	v_lshl_add_u64 v[4:5], s[0:1], 0, v[4:5]
	s_mov_b64 s[6:7], 0xc800000
	v_add_u32_e32 v30, s8, v33
	v_readfirstlane_b32 s58, v138
	s_lshl_b64 s[2:3], s[2:3], 12
	v_lshl_add_u64 v[28:29], v[4:5], 0, s[6:7]
	v_cmp_lt_i32_e64 s[46:47], -1, v30
	v_mov_b32_e32 v10, 0
	v_mov_b32_e32 v11, 0
	v_mov_b32_e32 v12, 0
	v_mov_b32_e32 v13, 0
	v_mov_b32_e32 v6, 0
	v_mov_b32_e32 v7, 0
	v_mov_b32_e32 v8, 0
	v_mov_b32_e32 v9, 0
	s_and_saveexec_b64 s[6:7], s[46:47]
	s_cbranch_execz .LBB0_818
	v_mov_b32_e32 v31, 0
	v_lshl_add_u64 v[4:5], s[2:3], 0, v[30:31]
	v_lshlrev_b64 v[4:5], 10, v[4:5]
	v_lshl_add_u64 v[4:5], v[28:29], 0, v[4:5]
	global_load_dwordx4 v[10:13], v[4:5], off
	global_load_dwordx4 v[6:9], v[4:5], off offset:512

.LBB0_1002:
	s_or_b64 exec, exec, s[8:9]
	v_mov_b32_e32 v2, 0
	global_load_dword v3, v2, s[2:3] sc1
	buffer_inv sc1
	s_waitcnt vmcnt(0)
	v_cmp_lt_u32_e32 vcc, 43, v3
	s_cbranch_vccnz .LBB0_1013
	s_add_u32 s4, s4, 0x1000000
	s_addc_u32 s5, s5, 0
	s_mov_b32 s12, 1
	s_branch .LBB0_1005

.LBB0_1011:
	s_andn2_b64 vcc, exec, s[8:9]
	s_cbranch_vccz .LBB0_1013
	v_mov_b32_e32 v2, 0
	v_mov_b32_e32 v3, 1
	global_store_dword v2, v3, s[4:5] sc1
.LBB0_1013:
	s_waitcnt vmcnt(0)
	s_waitcnt vmcnt(0)
.LBB0_1014:
	s_or_b64 exec, exec, s[0:1]
	s_mov_b64 s[0:1], s[82:83]
	v_mov_b32_e32 v2, v0
	s_mov_b32 s2, s73
	s_mov_b32 s5, s72
	s_barrier
	s_load_dwordx2 s[2:3], s[0:1], 0x90
	v_readfirstlane_b32 s4, v2
	s_lshl_b32 s0, s5, 3
	s_and_b32 s0, s0, 56
	s_bfe_u32 s1, s5, 0x30003
	s_ashr_i32 s4, s4, 3
	s_or_b32 s8, s0, s1
	s_and_b32 s1, s5, 0xffffffc0
	s_and_b32 s4, s4, -8
	s_lshl_b32 s0, s8, 8
	s_add_i32 s4, s1, s4
	s_add_i32 s6, s4, s0
	s_ashr_i32 s7, s6, 31
	s_lshl_b64 s[0:1], s[6:7], 11
	v_and_b32_e32 v126, 63, v2
	s_waitcnt lgkmcnt(0)
	s_add_u32 s0, s2, s0
	s_addc_u32 s1, s3, s1
	v_lshlrev_b32_e32 v30, 4, v126
	v_mov_b32_e32 v31, 0
	v_lshl_add_u64 v[2:3], s[0:1], 0, v[30:31]
	s_mov_b32 s0, 0x3001000
	v_add_co_u32_e32 v60, vcc, s0, v2
	s_mov_b64 s[0:1], 0x3000000
	s_nop 0
	v_addc_co_u32_e32 v61, vcc, 0, v3, vcc
	global_load_dwordx4 v[18:21], v[60:61], off offset:-4096
	v_lshl_add_u64 v[4:5], v[2:3], 0, s[0:1]
	global_load_dwordx4 v[22:25], v[4:5], off offset:1024
	global_load_dwordx4 v[32:35], v[4:5], off offset:2048
	global_load_dwordx4 v[36:39], v[4:5], off offset:3072
	s_mov_b32 s0, 0x3002000
	v_add_co_u32_e32 v62, vcc, s0, v2
	s_mov_b32 s1, 0x3003000
	s_nop 0
	v_addc_co_u32_e32 v63, vcc, 0, v3, vcc
	v_add_co_u32_e32 v64, vcc, s1, v2
	s_lshl_b32 s5, s8, 19
	s_nop 0
	v_addc_co_u32_e32 v65, vcc, 0, v3, vcc
	global_load_dwordx4 v[40:43], v[60:61], off
	global_load_dwordx4 v[44:47], v[60:61], off offset:1024
	global_load_dwordx4 v[48:51], v[60:61], off offset:2048
	global_load_dwordx4 v[52:55], v[60:61], off offset:3072
	global_load_dwordx4 v[56:59], v[64:65], off offset:-4096
	global_load_dwordx4 v[26:29], v[62:63], off offset:1024
	global_load_dwordx4 v[14:17], v[62:63], off offset:2048
	global_load_dwordx4 v[10:13], v[62:63], off offset:3072
	global_load_dwordx4 v[6:9], v[64:65], off
	global_load_dwordx4 v[2:5], v[64:65], off offset:1024
	s_add_u32 s5, s2, s5
	s_addc_u32 s8, s3, 0
	s_lshl_b32 s4, s4, 10
	s_and_b32 s0, s4, 0x3e000
	s_add_u32 s4, s5, s0
	s_addc_u32 s5, s8, 0
	s_mov_b32 s9, 0x42fe0000
	s_lshl_b64 s[0:1], s[6:7], 2
	s_add_u32 s0, s2, s0
	s_addc_u32 s1, s3, s1
	s_add_u32 s0, s0, 0xfc00000
	s_addc_u32 s1, s1, 0
	s_lshl_b64 s[6:7], s[6:7], 4
	s_mov_b32 s8, 0x40c0c00
	s_add_u32 s2, s2, s6
	s_mov_b32 s6, 0xa800000
	s_addc_u32 s3, s3, s7
	s_add_u32 s2, s2, 0xda00000
	s_addc_u32 s3, s3, 0
	s_waitcnt vmcnt(12)
	v_lshlrev_b32_e32 v148, 16, v22
	v_lshlrev_b32_e32 v140, 16, v18
	v_and_b32_e32 v141, 0xffff0000, v18
	v_lshlrev_b32_e32 v142, 16, v19
	v_and_b32_e32 v143, 0xffff0000, v19
	v_max3_f32 v18, |v140|, 0, |v141|
	v_lshlrev_b32_e32 v144, 16, v20
	v_and_b32_e32 v145, 0xffff0000, v20
	v_max3_f32 v18, v18, |v142|, |v143|
	v_lshlrev_b32_e32 v146, 16, v21
	v_and_b32_e32 v147, 0xffff0000, v21
	v_max3_f32 v18, v18, |v144|, |v145|
	v_and_b32_e32 v149, 0xffff0000, v22
	v_max3_f32 v18, v18, |v146|, |v147|
	v_lshlrev_b32_e32 v134, 16, v23
	v_and_b32_e32 v132, 0xffff0000, v23
	v_max3_f32 v18, v18, |v148|, |v149|
	v_lshlrev_b32_e32 v150, 16, v24
	v_and_b32_e32 v151, 0xffff0000, v24
	v_max3_f32 v18, v18, |v134|, |v132|
	v_lshlrev_b32_e32 v133, 16, v25
	v_and_b32_e32 v131, 0xffff0000, v25
	v_max3_f32 v18, v18, |v150|, |v151|
	v_max3_f32 v18, v18, |v133|, |v131|
	ds_swizzle_b32 v19, v18 offset:swizzle(SWAP,1)
	s_waitcnt vmcnt(11)
	v_lshlrev_b32_e32 v130, 16, v32
	v_and_b32_e32 v128, 0xffff0000, v32
	v_lshlrev_b32_e32 v122, 16, v33
	v_and_b32_e32 v119, 0xffff0000, v33
	s_waitcnt lgkmcnt(0)
	v_max_f32_e32 v19, v19, v19
	v_max_f32_e32 v18, v18, v19
	ds_swizzle_b32 v19, v18 offset:swizzle(SWAP,2)
	v_max3_f32 v20, |v130|, 0, |v128|
	v_lshlrev_b32_e32 v129, 16, v34
	v_and_b32_e32 v127, 0xffff0000, v34
	v_max3_f32 v20, v20, |v122|, |v119|
	s_waitcnt lgkmcnt(0)
	v_max_f32_e32 v19, v19, v19
	v_max_f32_e32 v18, v18, v19
	ds_swizzle_b32 v19, v18 offset:swizzle(SWAP,4)
	v_lshlrev_b32_e32 v123, 16, v35
	v_and_b32_e32 v121, 0xffff0000, v35
	v_max3_f32 v20, v20, |v129|, |v127|
	s_waitcnt vmcnt(10)
	v_lshlrev_b32_e32 v117, 16, v36
	s_waitcnt lgkmcnt(0)
	v_max_f32_e32 v19, v19, v19
	v_max_f32_e32 v18, v18, v19
	ds_swizzle_b32 v19, v18 offset:swizzle(SWAP,8)
	v_and_b32_e32 v116, 0xffff0000, v36
	v_max3_f32 v20, v20, |v123|, |v121|
	v_lshlrev_b32_e32 v113, 16, v37
	v_and_b32_e32 v114, 0xffff0000, v37
	s_waitcnt lgkmcnt(0)
	v_max_f32_e32 v19, v19, v19
	v_max_f32_e32 v30, v18, v19
	v_max3_f32 v18, v20, |v117|, |v116|
	v_lshlrev_b32_e32 v120, 16, v38
	v_and_b32_e32 v118, 0xffff0000, v38
	v_max3_f32 v18, v18, |v113|, |v114|
	v_lshlrev_b32_e32 v115, 16, v39
	v_and_b32_e32 v112, 0xffff0000, v39
	v_max3_f32 v18, v18, |v120|, |v118|
	ds_swizzle_b32 v32, v30 offset:swizzle(SWAP,16)
	v_max3_f32 v33, v18, |v115|, |v112|
	ds_swizzle_b32 v34, v33 offset:swizzle(SWAP,1)
	s_waitcnt vmcnt(9)
	v_lshlrev_b32_e32 v111, 16, v40
	v_and_b32_e32 v109, 0xffff0000, v40
	s_waitcnt lgkmcnt(1)
	v_max_f32_e32 v32, v32, v32
	v_max_f32_e32 v30, v30, v32
	s_waitcnt lgkmcnt(0)
	v_max_f32_e32 v32, v34, v34
	v_max_f32_e32 v32, v33, v32
	v_lshlrev_b32_e32 v106, 16, v41
	v_and_b32_e32 v105, 0xffff0000, v41
	v_max3_f32 v35, |v111|, 0, |v109|
	global_load_dwordx4 v[22:25], v[64:65], off offset:2048
	global_load_dwordx4 v[18:21], v[64:65], off offset:3072
	ds_swizzle_b32 v33, v32 offset:swizzle(SWAP,2)
	v_lshlrev_b32_e32 v110, 16, v42
	v_and_b32_e32 v108, 0xffff0000, v42
	v_max3_f32 v35, v35, |v106|, |v105|
	v_lshlrev_b32_e32 v107, 16, v43
	v_and_b32_e32 v104, 0xffff0000, v43
	v_max3_f32 v35, v35, |v110|, |v108|
	v_max3_f32 v35, v35, |v107|, |v104|
	s_waitcnt vmcnt(10)
	v_lshlrev_b32_e32 v103, 16, v44
	v_and_b32_e32 v101, 0xffff0000, v44
	v_lshlrev_b32_e32 v99, 16, v45
	v_and_b32_e32 v95, 0xffff0000, v45
	v_max3_f32 v35, v35, |v103|, |v101|
	v_lshlrev_b32_e32 v102, 16, v46
	v_and_b32_e32 v100, 0xffff0000, v46
	v_max3_f32 v35, v35, |v99|, |v95|
	s_waitcnt lgkmcnt(0)
	v_max_f32_e32 v33, v33, v33
	v_lshlrev_b32_e32 v98, 16, v47
	v_and_b32_e32 v94, 0xffff0000, v47
	v_max3_f32 v35, v35, |v102|, |v100|
	v_max_f32_e32 v32, v32, v33
	v_max3_f32 v35, v35, |v98|, |v94|
	ds_swizzle_b32 v33, v32 offset:swizzle(SWAP,4)
	ds_swizzle_b32 v36, v35 offset:swizzle(SWAP,1)
	v_mov_b32_e32 v34, v30
	s_nop 1
	v_permlane32_swap_b32_e32 v30, v34
	s_waitcnt lgkmcnt(1)
	v_max_f32_e32 v33, v33, v33
	s_waitcnt lgkmcnt(0)
	v_max_f32_e32 v36, v36, v36
	v_max_f32_e32 v32, v32, v33
	v_max_f32_e32 v35, v35, v36
	ds_swizzle_b32 v33, v32 offset:swizzle(SWAP,8)
	ds_swizzle_b32 v36, v35 offset:swizzle(SWAP,2)
	v_max_f32_e32 v34, v34, v34
	v_max_f32_e32 v30, v30, v30
	v_max_f32_e32 v137, v30, v34
	s_waitcnt lgkmcnt(1)
	v_max_f32_e32 v30, v33, v33
	s_waitcnt lgkmcnt(0)
	v_max_f32_e32 v33, v36, v36
	s_waitcnt vmcnt(9)
	v_lshlrev_b32_e32 v93, 16, v48
	v_and_b32_e32 v91, 0xffff0000, v48
	v_max_f32_e32 v33, v35, v33
	v_lshlrev_b32_e32 v89, 16, v49
	v_and_b32_e32 v87, 0xffff0000, v49
	v_max3_f32 v35, |v93|, 0, |v91|
	v_lshlrev_b32_e32 v92, 16, v50
	v_and_b32_e32 v90, 0xffff0000, v50
	v_max3_f32 v35, v35, |v89|, |v87|
	v_lshlrev_b32_e32 v88, 16, v51
	v_and_b32_e32 v86, 0xffff0000, v51
	v_max3_f32 v35, v35, |v92|, |v90|
	v_max3_f32 v35, v35, |v88|, |v86|
	s_waitcnt vmcnt(8)
	v_lshlrev_b32_e32 v85, 16, v52
	v_and_b32_e32 v83, 0xffff0000, v52
	v_lshlrev_b32_e32 v81, 16, v53
	v_and_b32_e32 v79, 0xffff0000, v53
	v_max3_f32 v35, v35, |v85|, |v83|
	v_lshlrev_b32_e32 v84, 16, v54
	v_and_b32_e32 v82, 0xffff0000, v54
	v_max3_f32 v35, v35, |v81|, |v79|
	v_lshlrev_b32_e32 v80, 16, v55
	v_and_b32_e32 v78, 0xffff0000, v55
	v_max3_f32 v35, v35, |v84|, |v82|
	ds_swizzle_b32 v34, v33 offset:swizzle(SWAP,4)
	v_max3_f32 v35, v35, |v80|, |v78|
	ds_swizzle_b32 v36, v35 offset:swizzle(SWAP,1)
	v_max_f32_e32 v30, v32, v30
	ds_swizzle_b32 v32, v30 offset:swizzle(SWAP,16)
	s_waitcnt lgkmcnt(2)
	v_max_f32_e32 v34, v34, v34
	v_max_f32_e32 v33, v33, v34
	s_waitcnt lgkmcnt(1)
	v_max_f32_e32 v36, v36, v36
	ds_swizzle_b32 v34, v33 offset:swizzle(SWAP,8)
	v_max_f32_e32 v35, v35, v36
	ds_swizzle_b32 v36, v35 offset:swizzle(SWAP,2)
	s_waitcnt lgkmcnt(2)
	v_max_f32_e32 v32, v32, v32
	v_max_f32_e32 v138, v30, v32
	s_waitcnt lgkmcnt(1)
	v_max_f32_e32 v30, v34, v34
	v_max_f32_e32 v30, v33, v30
	s_waitcnt lgkmcnt(0)
	v_max_f32_e32 v33, v36, v36
	s_waitcnt vmcnt(7)
	v_lshlrev_b32_e32 v77, 16, v56
	v_and_b32_e32 v75, 0xffff0000, v56
	v_max_f32_e32 v33, v35, v33
	v_lshlrev_b32_e32 v72, 16, v57
	v_and_b32_e32 v71, 0xffff0000, v57
	v_max3_f32 v35, |v77|, 0, |v75|
	v_lshlrev_b32_e32 v76, 16, v58
	v_and_b32_e32 v74, 0xffff0000, v58
	v_max3_f32 v35, v35, |v72|, |v71|
	v_lshlrev_b32_e32 v73, 16, v59
	v_and_b32_e32 v70, 0xffff0000, v59
	v_max3_f32 v35, v35, |v76|, |v74|
	v_max3_f32 v35, v35, |v73|, |v70|
	s_waitcnt vmcnt(6)
	v_lshlrev_b32_e32 v69, 16, v26
	v_and_b32_e32 v67, 0xffff0000, v26
	v_lshlrev_b32_e32 v65, 16, v27
	v_and_b32_e32 v63, 0xffff0000, v27
	v_max3_f32 v26, v35, |v69|, |v67|
	v_lshlrev_b32_e32 v68, 16, v28
	v_and_b32_e32 v66, 0xffff0000, v28
	v_max3_f32 v26, v26, |v65|, |v63|
	v_lshlrev_b32_e32 v64, 16, v29
	v_and_b32_e32 v62, 0xffff0000, v29
	v_max3_f32 v26, v26, |v68|, |v66|
	v_max3_f32 v26, v26, |v64|, |v62|
	s_waitcnt vmcnt(5)
	v_lshlrev_b32_e32 v61, 16, v14
	v_and_b32_e32 v59, 0xffff0000, v14
	ds_swizzle_b32 v27, v26 offset:swizzle(SWAP,1)
	v_lshlrev_b32_e32 v57, 16, v15
	v_and_b32_e32 v55, 0xffff0000, v15
	v_max3_f32 v14, |v61|, 0, |v59|
	v_lshlrev_b32_e32 v60, 16, v16
	v_and_b32_e32 v58, 0xffff0000, v16
	v_max3_f32 v14, v14, |v57|, |v55|
	v_lshlrev_b32_e32 v56, 16, v17
	v_and_b32_e32 v54, 0xffff0000, v17
	v_max3_f32 v14, v14, |v60|, |v58|
	v_max3_f32 v14, v14, |v56|, |v54|
	s_waitcnt vmcnt(4)
	v_lshlrev_b32_e32 v53, 16, v10
	v_and_b32_e32 v51, 0xffff0000, v10
	v_lshlrev_b32_e32 v49, 16, v11
	v_and_b32_e32 v47, 0xffff0000, v11
	v_max3_f32 v10, v14, |v53|, |v51|
	s_waitcnt lgkmcnt(0)
	v_max_f32_e32 v27, v27, v27
	v_lshlrev_b32_e32 v52, 16, v12
	v_and_b32_e32 v50, 0xffff0000, v12
	v_max3_f32 v10, v10, |v49|, |v47|
	v_max_f32_e32 v26, v26, v27
	v_lshlrev_b32_e32 v48, 16, v13
	v_and_b32_e32 v46, 0xffff0000, v13
	v_max3_f32 v10, v10, |v52|, |v50|
	ds_swizzle_b32 v27, v26 offset:swizzle(SWAP,2)
	v_max3_f32 v10, v10, |v48|, |v46|
	ds_swizzle_b32 v11, v10 offset:swizzle(SWAP,1)
	ds_swizzle_b32 v34, v33 offset:swizzle(SWAP,4)
	ds_swizzle_b32 v32, v30 offset:swizzle(SWAP,16)
	s_waitcnt lgkmcnt(3)
	v_max_f32_e32 v27, v27, v27
	v_max_f32_e32 v26, v26, v27
	s_waitcnt lgkmcnt(2)
	v_max_f32_e32 v11, v11, v11
	ds_swizzle_b32 v27, v26 offset:swizzle(SWAP,4)
	v_max_f32_e32 v10, v10, v11
	ds_swizzle_b32 v11, v10 offset:swizzle(SWAP,2)
	s_waitcnt lgkmcnt(3)
	v_max_f32_e32 v34, v34, v34
	v_max_f32_e32 v33, v33, v34
	ds_swizzle_b32 v34, v33 offset:swizzle(SWAP,8)
	s_waitcnt lgkmcnt(2)
	v_max_f32_e32 v12, v27, v27
	v_max_f32_e32 v12, v26, v12
	s_waitcnt lgkmcnt(1)
	v_max_f32_e32 v11, v11, v11
	ds_swizzle_b32 v13, v12 offset:swizzle(SWAP,8)
	v_max_f32_e32 v10, v10, v11
	ds_swizzle_b32 v11, v10 offset:swizzle(SWAP,4)
	s_waitcnt lgkmcnt(2)
	v_max_f32_e32 v28, v34, v34
	v_max_f32_e32 v28, v33, v28
	ds_swizzle_b32 v29, v28 offset:swizzle(SWAP,16)
	s_waitcnt lgkmcnt(2)
	v_max_f32_e32 v13, v13, v13
	v_max_f32_e32 v12, v12, v13
	s_waitcnt lgkmcnt(1)
	v_max_f32_e32 v11, v11, v11
	ds_swizzle_b32 v13, v12 offset:swizzle(SWAP,16)
	v_max_f32_e32 v10, v10, v11
	ds_swizzle_b32 v11, v10 offset:swizzle(SWAP,8)
	s_waitcnt vmcnt(3)
	v_lshlrev_b32_e32 v45, 16, v6
	v_and_b32_e32 v43, 0xffff0000, v6
	v_max_f32_e32 v32, v32, v32
	s_waitcnt lgkmcnt(2)
	v_max_f32_e32 v29, v29, v29
	v_lshlrev_b32_e32 v40, 16, v7
	v_and_b32_e32 v39, 0xffff0000, v7
	v_max3_f32 v6, |v45|, 0, |v43|
	s_waitcnt vmcnt(1)
	v_lshlrev_b32_e32 v27, 16, v22
	v_and_b32_e32 v26, 0xffff0000, v22
	v_max_f32_e32 v135, v30, v32
	v_max_f32_e32 v124, v28, v29
	v_lshlrev_b32_e32 v44, 16, v8
	v_and_b32_e32 v42, 0xffff0000, v8
	v_max3_f32 v6, v6, |v40|, |v39|
	v_lshlrev_b32_e32 v32, 16, v5
	v_and_b32_e32 v28, 0xffff0000, v5
	v_lshlrev_b32_e32 v17, 16, v23
	v_and_b32_e32 v15, 0xffff0000, v23
	v_max3_f32 v5, |v27|, 0, |v26|
	v_lshlrev_b32_e32 v41, 16, v9
	v_and_b32_e32 v38, 0xffff0000, v9
	v_max3_f32 v6, v6, |v44|, |v42|
	v_lshlrev_b32_e32 v23, 16, v24
	v_and_b32_e32 v22, 0xffff0000, v24
	v_max3_f32 v5, v5, |v17|, |v15|
	s_waitcnt lgkmcnt(1)
	v_max_f32_e32 v13, v13, v13
	v_max3_f32 v6, v6, |v41|, |v38|
	v_lshlrev_b32_e32 v37, 16, v2
	v_and_b32_e32 v35, 0xffff0000, v2
	v_lshlrev_b32_e32 v16, 16, v25
	v_and_b32_e32 v14, 0xffff0000, v25
	v_max3_f32 v5, v5, |v23|, |v22|
	v_max_f32_e32 v96, v12, v13
	v_lshlrev_b32_e32 v33, 16, v3
	v_and_b32_e32 v29, 0xffff0000, v3
	v_lshlrev_b32_e32 v36, 16, v4
	v_and_b32_e32 v34, 0xffff0000, v4
	v_max3_f32 v2, v6, |v37|, |v35|
	s_waitcnt lgkmcnt(0)
	v_max_f32_e32 v4, v11, v11
	v_max3_f32 v5, v5, |v16|, |v14|
	s_waitcnt vmcnt(0)
	v_lshlrev_b32_e32 v13, 16, v18
	v_and_b32_e32 v11, 0xffff0000, v18
	v_max3_f32 v2, v2, |v33|, |v29|
	v_lshlrev_b32_e32 v9, 16, v19
	v_and_b32_e32 v7, 0xffff0000, v19
	v_max3_f32 v5, v5, |v13|, |v11|
	v_max3_f32 v2, v2, |v36|, |v34|
	v_max_f32_e32 v4, v10, v4
	v_lshlrev_b32_e32 v12, 16, v20
	v_and_b32_e32 v10, 0xffff0000, v20
	v_max3_f32 v5, v5, |v9|, |v7|
	v_max3_f32 v2, v2, |v32|, |v28|
	v_lshlrev_b32_e32 v8, 16, v21
	v_and_b32_e32 v6, 0xffff0000, v21
	v_max3_f32 v5, v5, |v12|, |v10|
	ds_swizzle_b32 v3, v2 offset:swizzle(SWAP,1)
	v_max3_f32 v5, v5, |v8|, |v6|
	ds_swizzle_b32 v18, v5 offset:swizzle(SWAP,1)
	ds_swizzle_b32 v19, v4 offset:swizzle(SWAP,16)
	v_lshlrev_b32_e32 v30, 3, v126
	s_waitcnt lgkmcnt(2)
	v_max_f32_e32 v3, v3, v3
	v_max_f32_e32 v2, v2, v3
	s_waitcnt lgkmcnt(1)
	v_max_f32_e32 v18, v18, v18
	ds_swizzle_b32 v3, v2 offset:swizzle(SWAP,2)
	v_max_f32_e32 v5, v5, v18
	ds_swizzle_b32 v18, v5 offset:swizzle(SWAP,2)
	s_waitcnt lgkmcnt(2)
	v_max_f32_e32 v19, v19, v19
	v_max_f32_e32 v24, v4, v19
	s_waitcnt lgkmcnt(1)
	v_max_f32_e32 v3, v3, v3
	v_max_f32_e32 v2, v2, v3
	s_waitcnt lgkmcnt(0)
	v_max_f32_e32 v18, v18, v18
	ds_swizzle_b32 v3, v2 offset:swizzle(SWAP,4)
	v_max_f32_e32 v5, v5, v18
	ds_swizzle_b32 v18, v5 offset:swizzle(SWAP,4)
	v_mov_b32_e32 v139, v138
	v_mov_b32_e32 v136, v135
	s_waitcnt lgkmcnt(1)
	v_max_f32_e32 v3, v3, v3
	v_max_f32_e32 v2, v2, v3
	s_waitcnt lgkmcnt(0)
	v_max_f32_e32 v4, v18, v18
	ds_swizzle_b32 v3, v2 offset:swizzle(SWAP,8)
	v_max_f32_e32 v4, v5, v4
	ds_swizzle_b32 v5, v4 offset:swizzle(SWAP,8)
	v_mov_b32_e32 v125, v124
	v_mov_b32_e32 v97, v96
	s_waitcnt lgkmcnt(1)
	v_max_f32_e32 v3, v3, v3
	v_max_f32_e32 v2, v2, v3
	s_waitcnt lgkmcnt(0)
	v_max_f32_e32 v5, v5, v5
	ds_swizzle_b32 v3, v2 offset:swizzle(SWAP,16)
	v_max_f32_e32 v4, v4, v5
	ds_swizzle_b32 v5, v4 offset:swizzle(SWAP,16)
	v_mov_b32_e32 v25, v24
	v_permlane32_swap_b32_e32 v138, v139
	s_waitcnt lgkmcnt(1)
	v_max_f32_e32 v3, v3, v3
	v_max_f32_e32 v20, v2, v3
	s_waitcnt lgkmcnt(0)
	v_max_f32_e32 v2, v5, v5
	v_max_f32_e32 v18, v4, v2
	v_lshl_add_u64 v[4:5], s[4:5], 0, v[30:31]
	v_div_scale_f32 v30, s[4:5], v137, v137, s9
	v_rcp_f32_e32 v152, v30
	s_mov_b64 s[4:5], 0xa800000
	v_lshl_add_u64 v[2:3], v[4:5], 0, s[4:5]
	v_cmp_eq_u32_e64 s[4:5], 0, v126
	v_fma_f32 v126, -v30, v152, 1.0
	v_fmac_f32_e32 v152, v126, v152
	v_div_scale_f32 v126, vcc, s9, v137, s9
	v_mul_f32_e32 v153, v126, v152
	v_fma_f32 v154, -v30, v153, v126
	v_fmac_f32_e32 v153, v154, v152
	v_fma_f32 v30, -v30, v153, v126
	v_div_fmas_f32 v30, v30, v152, v153
	v_div_fixup_f32 v30, v30, v137, s9
	v_cmp_lt_f32_e32 vcc, 0, v137
	v_mov_b32_e32 v21, v20
	v_mov_b32_e32 v19, v18
	v_cndmask_b32_e32 v30, 0, v30, vcc
	v_mul_f32_e32 v126, v30, v140
	v_mul_f32_e32 v140, v30, v141
	v_rndne_f32_e32 v140, v140
	v_mul_f32_e32 v141, v30, v144
	v_mul_f32_e32 v144, v30, v145
	v_mul_f32_e32 v142, v30, v142
	v_mul_f32_e32 v143, v30, v143
	v_rndne_f32_e32 v126, v126
	v_cvt_i32_f32_e32 v140, v140
	v_rndne_f32_e32 v144, v144
	v_rndne_f32_e32 v142, v142
	v_mul_f32_e32 v145, v30, v146
	v_rndne_f32_e32 v143, v143
	v_mul_f32_e32 v146, v30, v147
	v_cvt_i32_f32_e32 v126, v126
	v_rndne_f32_e32 v141, v141
	v_cvt_i32_f32_e32 v144, v144
	v_cvt_i32_f32_sdwa v142, v142 dst_sel:WORD_1 dst_unused:UNUSED_PAD src0_sel:DWORD
	v_rndne_f32_e32 v145, v145
	v_cvt_i32_f32_e32 v143, v143
	v_rndne_f32_e32 v146, v146
	v_cvt_i32_f32_e32 v141, v141
	v_cvt_i32_f32_sdwa v145, v145 dst_sel:WORD_1 dst_unused:UNUSED_PAD src0_sel:DWORD
	v_cvt_i32_f32_e32 v146, v146
	v_lshlrev_b32_e32 v140, 8, v140
	v_and_b32_e32 v140, 0xff00, v140
	v_lshlrev_b32_e32 v144, 8, v144
	v_and_b32_e32 v142, 0xff0000, v142
	v_perm_b32 v126, v143, v126, s8
	v_and_b32_e32 v144, 0xff00, v144
	v_and_b32_e32 v145, 0xff0000, v145
	v_or3_b32 v140, v126, v140, v142
	v_perm_b32 v126, v146, v141, s8
	v_add_co_u32_e32 v4, vcc, s6, v4
	v_or3_b32 v141, v126, v144, v145
	s_nop 0
	v_addc_co_u32_e32 v5, vcc, 0, v5, vcc
	global_store_dwordx2 v[4:5], v[140:141], off
	v_mul_f32_e32 v5, v30, v149
	v_mul_f32_e32 v4, v30, v148
	v_rndne_f32_e32 v5, v5
	v_mul_f32_e32 v140, v30, v151
	v_mul_f32_e32 v134, v30, v134
	v_mul_f32_e32 v132, v30, v132
	v_rndne_f32_e32 v4, v4
	v_cvt_i32_f32_e32 v5, v5
	v_mul_f32_e32 v126, v30, v150
	v_rndne_f32_e32 v140, v140
	v_rndne_f32_e32 v134, v134
	v_mul_f32_e32 v133, v30, v133
	v_rndne_f32_e32 v132, v132
	v_mul_f32_e32 v30, v30, v131
	v_cvt_i32_f32_e32 v4, v4
	v_rndne_f32_e32 v126, v126
	v_cvt_i32_f32_e32 v140, v140
	v_cvt_i32_f32_sdwa v134, v134 dst_sel:WORD_1 dst_unused:UNUSED_PAD src0_sel:DWORD
	v_rndne_f32_e32 v133, v133
	v_cvt_i32_f32_e32 v132, v132
	v_rndne_f32_e32 v30, v30
	v_cvt_i32_f32_e32 v126, v126
	v_cvt_i32_f32_sdwa v133, v133 dst_sel:WORD_1 dst_unused:UNUSED_PAD src0_sel:DWORD
	v_cvt_i32_f32_e32 v30, v30
	v_lshlrev_b32_e32 v5, 8, v5
	v_and_b32_e32 v5, 0xff00, v5
	v_lshlrev_b32_e32 v140, 8, v140
	v_and_b32_e32 v134, 0xff0000, v134
	v_perm_b32 v4, v132, v4, s8
	v_and_b32_e32 v140, 0xff00, v140
	v_and_b32_e32 v131, 0xff0000, v133
	v_or3_b32 v4, v4, v5, v134
	v_perm_b32 v5, v30, v126, s8
	v_permlane32_swap_b32_e32 v135, v136
	v_permlane32_swap_b32_e32 v124, v125
	v_permlane32_swap_b32_e32 v96, v97
	v_permlane32_swap_b32_e32 v24, v25
	v_permlane32_swap_b32_e32 v20, v21
	v_permlane32_swap_b32_e32 v18, v19
	v_or3_b32 v5, v5, v140, v131
	global_store_dwordx2 v[2:3], v[4:5], off offset:512
	s_and_saveexec_b64 s[6:7], s[4:5]
	s_cbranch_execz .LBB0_1016
	global_load_dwordx4 v[140:143], v31, s[2:3]
	s_waitcnt vmcnt(0)
	v_mov_b32_e32 v4, v141
	v_mov_b32_e32 v5, v142
	v_mov_b32_e32 v141, v143
	v_pk_add_f32 v[4:5], v[4:5], v[140:141]
	s_nop 0
	v_add_f32_e32 v4, v4, v5
	v_mov_b32_e32 v5, 0x358637bd
	v_fmac_f32_e32 v5, 0x3a800000, v4
	v_rsq_f32_e32 v4, v5
	v_mul_f32_e32 v5, 0x3c010204, v137
	v_mul_f32_e32 v4, v5, v4
	global_store_dword v31, v4, s[0:1]
